# write-through (sc1) on the full-line streaming stores of conv_pass / pooling / ffn_elementwise only, so the grid barrier's L2 write-back after those phases has less to flush
# speedup vs baseline: 1.0009x; 1.0009x over previous
; __device__ __forceinline__ float siluf_(float x) { return x * sigmoidf_(x); }
; __device__ __forceinline__ void conv_pass(const Ctx& C_, int l) {
;     ...
;             float oacc[4][8];
; #pragma unroll
;             for (int i = 0; i < 11; ++i) {
;                 float xv[8]; unpack8(raw[i], xv);
;                 if (i < 8) {
; #pragma unroll
;                     for (int e = 0; e < 8; ++e) oacc[i & 3][e] = 0.f;
;                 }
; #pragma unroll
;                 for (int k = 0; k < 4; ++k) { const int j = i - k;
;                     if (j >= 0 && j < 8) { float* o = oacc[j & 3];
;                         o[0] += cw[k][0].x * xv[0]; o[1] += cw[k][0].y * xv[1]; o[2] += cw[k][0].z * xv[2]; o[3] += cw[k][0].w * xv[3];
;                         o[4] += cw[k][1].x * xv[4]; o[5] += cw[k][1].y * xv[5]; o[6] += cw[k][1].z * xv[6]; o[7] += cw[k][1].w * xv[7]; } }
;                 if (i >= 3) {
;                     const int j = i - 3; const float* oa = oacc[j & 3];
;                     float o[8];
;                     o[0] = siluf_(oa[0] + cbias[0].x); o[1] = siluf_(oa[1] + cbias[0].y); o[2] = siluf_(oa[2] + cbias[0].z); o[3] = siluf_(oa[3] + cbias[0].w);
;                     o[4] = siluf_(oa[4] + cbias[1].x); o[5] = siluf_(oa[5] + cbias[1].y); o[6] = siluf_(oa[6] + cbias[1].z); o[7] = siluf_(oa[7] + cbias[1].w);
;                     *(u32x4*)(L_XBCC + (size_t)(m0 + j) * CONVD + ch) = pack8(o);
.LBB0_355:
	s_or_b64 exec, exec, s[20:21]
	s_waitcnt vmcnt(9)
	v_lshlrev_b32_e32 v138, 16, v106
	v_lshlrev_b32_e32 v139, 16, v110
	v_pk_mul_f32 v[140:141], v[136:137], v[138:139]
	v_and_b32_e32 v143, 0xffff0000, v110
	v_add_f32_e32 v139, 0, v141
	v_and_b32_e32 v142, 0xffff0000, v106
	v_add_f32_e32 v139, v140, v139
	v_pk_mul_f32 v[140:141], v[18:19], v[142:143]
	v_lshlrev_b32_e32 v148, 16, v107
	v_add_f32_e32 v106, 0, v141
	v_lshlrev_b32_e32 v149, 16, v111
	v_add_f32_e32 v144, v140, v106
	v_pk_mul_f32 v[140:141], v[132:133], v[148:149]
	v_and_b32_e32 v111, 0xffff0000, v111
	v_add_f32_e32 v106, 0, v141
	v_and_b32_e32 v110, 0xffff0000, v107
	v_add_f32_e32 v149, v140, v106
	v_pk_mul_f32 v[106:107], v[20:21], v[110:111]
	v_lshlrev_b32_e32 v150, 16, v108
	v_add_f32_e32 v107, 0, v107
	v_lshlrev_b32_e32 v151, 16, v112
	v_add_f32_e32 v156, v106, v107
	v_pk_mul_f32 v[106:107], v[128:129], v[150:151]
	v_and_b32_e32 v153, 0xffff0000, v112
	v_add_f32_e32 v107, 0, v107
	v_and_b32_e32 v152, 0xffff0000, v108
	v_add_f32_e32 v157, v106, v107
	v_pk_mul_f32 v[106:107], v[22:23], v[152:153]
	v_lshlrev_b32_e32 v154, 16, v109
	v_add_f32_e32 v107, 0, v107
	v_lshlrev_b32_e32 v155, 16, v113
	v_add_f32_e32 v159, v106, v107
	v_pk_mul_f32 v[106:107], v[124:125], v[154:155]
	v_and_b32_e32 v161, 0xffff0000, v113
	v_add_f32_e32 v107, 0, v107
	v_and_b32_e32 v160, 0xffff0000, v109
	v_add_f32_e32 v155, v106, v107
	v_pk_mul_f32 v[106:107], v[24:25], v[160:161]
	s_waitcnt vmcnt(8)
	v_lshlrev_b32_e32 v141, 16, v102
	v_add_f32_e32 v107, 0, v107
	s_waitcnt vmcnt(7)
	v_lshlrev_b32_e32 v140, 16, v98
	v_add_f32_e32 v162, v106, v107
	v_pk_mov_b32 v[106:107], v[140:141], v[138:139] op_sel:[1,0]
	v_pk_mul_f32 v[108:109], v[136:137], v[140:141]
	v_pk_mul_f32 v[106:107], v[136:137], v[106:107]
	v_add_f32_e32 v109, 0, v109
	v_add_f32_e32 v107, 0, v107
	v_add_f32_e32 v163, v106, v107
	v_pk_mul_f32 v[106:107], v[134:135], v[140:141]
	v_add_f32_e32 v164, v108, v109
	v_add_f32_e32 v107, v107, v139
	v_add_f32_e32 v165, v106, v107
	v_and_b32_e32 v107, 0xffff0000, v102
	v_and_b32_e32 v106, 0xffff0000, v98
	v_pk_mov_b32 v[108:109], v[106:107], v[142:143] op_sel:[1,0]
	v_lshlrev_b32_e32 v145, 16, v103
	v_pk_mul_f32 v[108:109], v[18:19], v[108:109]
	v_and_b32_e32 v143, 0xffff0000, v103
	v_add_f32_e32 v98, 0, v109
	v_add_f32_e32 v166, v108, v98
	v_pk_mul_f32 v[108:109], v[10:11], v[106:107]
	v_and_b32_e32 v142, 0xffff0000, v99
	v_add_f32_e32 v98, v109, v144
	v_lshlrev_b32_e32 v144, 16, v99
	v_add_f32_e32 v168, v108, v98
	v_pk_mov_b32 v[108:109], v[144:145], v[148:149] op_sel:[1,0]
	v_pk_mul_f32 v[112:113], v[18:19], v[106:107]
	v_pk_mul_f32 v[108:109], v[132:133], v[108:109]
	v_add_f32_e32 v102, 0, v113
	v_add_f32_e32 v98, 0, v109
	v_add_f32_e32 v169, v108, v98
	v_pk_mul_f32 v[108:109], v[130:131], v[144:145]
	v_add_f32_e32 v167, v112, v102
	v_add_f32_e32 v98, v109, v149
	v_add_f32_e32 v148, v108, v98
	v_pk_mov_b32 v[98:99], v[142:143], v[110:111] op_sel:[1,0]
	v_pk_mul_f32 v[112:113], v[132:133], v[144:145]
	v_pk_mul_f32 v[98:99], v[20:21], v[98:99]
	v_add_f32_e32 v102, 0, v113
	v_add_f32_e32 v99, 0, v99
	v_add_f32_e32 v171, v98, v99
	v_pk_mul_f32 v[98:99], v[12:13], v[142:143]
	v_lshlrev_b32_e32 v139, 16, v104
	v_add_f32_e32 v99, v99, v156
	v_lshlrev_b32_e32 v138, 16, v100
	v_add_f32_e32 v170, v112, v102
	v_pk_mul_f32 v[102:103], v[20:21], v[142:143]
	v_add_f32_e32 v149, v98, v99
	v_pk_mov_b32 v[98:99], v[138:139], v[150:151] op_sel:[1,0]
	v_add_f32_e32 v103, 0, v103
	v_pk_mul_f32 v[98:99], v[128:129], v[98:99]
	v_add_f32_e32 v172, v102, v103
	v_add_f32_e32 v99, 0, v99
	v_pk_mul_f32 v[102:103], v[128:129], v[138:139]
	v_add_f32_e32 v151, v98, v99
	v_pk_mul_f32 v[98:99], v[126:127], v[138:139]
	v_add_f32_e32 v103, 0, v103
	v_add_f32_e32 v99, v99, v157
	v_add_f32_e32 v158, v102, v103
	v_and_b32_e32 v103, 0xffff0000, v104
	v_and_b32_e32 v102, 0xffff0000, v100
	v_add_f32_e32 v150, v98, v99
	v_pk_mov_b32 v[98:99], v[102:103], v[152:153] op_sel:[1,0]
	v_lshlrev_b32_e32 v113, 16, v105
	v_pk_mul_f32 v[98:99], v[22:23], v[98:99]
	v_lshlrev_b32_e32 v112, 16, v101
	v_add_f32_e32 v99, 0, v99
	v_add_f32_e32 v152, v98, v99
	v_pk_mul_f32 v[98:99], v[14:15], v[102:103]
	v_pk_mul_f32 v[108:109], v[22:23], v[102:103]
	v_add_f32_e32 v99, v99, v159
	v_add_f32_e32 v104, v98, v99
	v_pk_mov_b32 v[98:99], v[112:113], v[154:155] op_sel:[1,0]
	v_add_f32_e32 v100, 0, v109
	v_pk_mul_f32 v[98:99], v[124:125], v[98:99]
	v_add_f32_e32 v157, v108, v100
	v_add_f32_e32 v99, 0, v99
	v_add_f32_e32 v153, v98, v99
	v_pk_mul_f32 v[98:99], v[122:123], v[112:113]
	v_pk_mul_f32 v[108:109], v[124:125], v[112:113]
	v_add_f32_e32 v99, v99, v155
	v_add_f32_e32 v100, 0, v109
	v_and_b32_e32 v111, 0xffff0000, v105
	v_and_b32_e32 v110, 0xffff0000, v101
	v_add_f32_e32 v105, v2, v165
	v_add_f32_e32 v156, v108, v100
	v_add_f32_e32 v108, v98, v99
	v_pk_mov_b32 v[98:99], v[110:111], v[160:161] op_sel:[1,0]
	v_mul_f32_e32 v109, 0xbfb8aa3b, v105
	v_pk_mul_f32 v[98:99], v[24:25], v[98:99]
	v_exp_f32_e32 v109, v109
	v_add_f32_e32 v99, 0, v99
	v_add_f32_e32 v154, v98, v99
	v_pk_mul_f32 v[98:99], v[16:17], v[110:111]
	v_pk_mul_f32 v[100:101], v[24:25], v[110:111]
	v_add_f32_e32 v99, v99, v162
	v_add_f32_e32 v101, 0, v101
	v_add_f32_e32 v155, v100, v101
	v_add_f32_e32 v98, v98, v99
	v_add_f32_e32 v99, 1.0, v109
	v_add_f32_e32 v100, v3, v168
	v_add_f32_e32 v109, v4, v148
	v_mul_f32_e32 v101, 0xbfb8aa3b, v100
	v_mul_f32_e32 v148, 0xbfb8aa3b, v109
	v_exp_f32_e32 v101, v101
	v_exp_f32_e32 v148, v148
	v_add_f32_e32 v149, v5, v149
	v_mul_f32_e32 v159, 0xbfb8aa3b, v149
	v_add_f32_e32 v101, 1.0, v101
	v_add_f32_e32 v148, 1.0, v148
	v_rcp_f32_e32 v99, v99
	v_rcp_f32_e32 v101, v101
	v_rcp_f32_e32 v148, v148
	v_exp_f32_e32 v159, v159
	v_add_f32_e32 v104, v7, v104
	v_mul_f32_e32 v99, v105, v99
	v_mul_f32_e32 v100, v100, v101
	v_mul_f32_e32 v101, v109, v148
	v_add_f32_e32 v105, 1.0, v159
	v_add_f32_e32 v109, v6, v150
	v_mul_f32_e32 v150, 0xbfb8aa3b, v104
	v_rcp_f32_e32 v105, v105
	v_exp_f32_e32 v150, v150
	v_add_f32_e32 v108, v8, v108
	v_mul_f32_e32 v148, 0xbfb8aa3b, v109
	v_mul_f32_e32 v105, v149, v105
	v_add_f32_e32 v149, 1.0, v150
	v_mul_f32_e32 v150, 0xbfb8aa3b, v108
	v_add_f32_e32 v98, v9, v98
	v_exp_f32_e32 v148, v148
	v_exp_f32_e32 v150, v150
	v_mul_f32_e32 v159, 0xbfb8aa3b, v98
	v_exp_f32_e32 v159, v159
	v_add_f32_e32 v148, 1.0, v148
	v_add_f32_e32 v150, 1.0, v150
	v_rcp_f32_e32 v148, v148
	v_rcp_f32_e32 v149, v149
	v_rcp_f32_e32 v150, v150
	v_add_f32_e32 v159, 1.0, v159
	v_rcp_f32_e32 v159, v159
	s_and_b64 s[0:1], exec, s[2:3]
	v_mul_f32_e32 v109, v109, v148
	v_mul_f32_e32 v104, v104, v149
	v_mul_f32_e32 v108, v108, v150
	s_movk_i32 s2, 0x1800
	s_or_b64 s[18:19], s[0:1], s[18:19]
	v_mul_f32_e32 v148, v98, v159
	v_cvt_pk_bf16_f32 v98, v99, v100
	v_cvt_pk_bf16_f32 v99, v101, v105
	v_cvt_pk_bf16_f32 v100, v109, v104
	v_cvt_pk_bf16_f32 v101, v108, v148
	v_mad_i64_i32 v[104:105], s[0:1], v147, s2, v[120:121]
	s_waitcnt vmcnt(6)
; __device__ __forceinline__ float siluf_(float x) { return x * sigmoidf_(x); }
; __device__ __forceinline__ void conv_pass(const Ctx& C_, int l) {
;     ...
;                 for (int k = 0; k < 4; ++k) { const int j = i - k;
;                     if (j >= 0 && j < 8) { float* o = oacc[j & 3];
;                         o[0] += cw[k][0].x * xv[0]; o[1] += cw[k][0].y * xv[1]; o[2] += cw[k][0].z * xv[2]; o[3] += cw[k][0].w * xv[3];
;                         o[4] += cw[k][1].x * xv[4]; o[5] += cw[k][1].y * xv[5]; o[6] += cw[k][1].z * xv[6]; o[7] += cw[k][1].w * xv[7]; } }
;                 if (i >= 3) {
;                     const int j = i - 3; const float* oa = oacc[j & 3];
;                     float o[8];
;                     o[0] = siluf_(oa[0] + cbias[0].x); o[1] = siluf_(oa[1] + cbias[0].y); o[2] = siluf_(oa[2] + cbias[0].z); o[3] = siluf_(oa[3] + cbias[0].w);
;                     o[4] = siluf_(oa[4] + cbias[1].x); o[5] = siluf_(oa[5] + cbias[1].y); o[6] = siluf_(oa[6] + cbias[1].z); o[7] = siluf_(oa[7] + cbias[1].w);
;                     *(u32x4*)(L_XBCC + (size_t)(m0 + j) * CONVD + ch) = pack8(o);
;                 }
	v_lshlrev_b32_e32 v109, 16, v94
	s_waitcnt vmcnt(5)
	v_lshlrev_b32_e32 v108, 16, v90
	global_store_dwordx4 v[104:105], v[98:101], off sc1
	v_add_u32_e32 v104, -6, v115
	s_movk_i32 s53, 0x1800
	v_pk_mov_b32 v[98:99], v[108:109], v[140:141] op_sel:[1,0]
	v_mad_i64_i32 v[140:141], s[0:1], v104, s2, v[120:121]
	v_pk_mul_f32 v[100:101], v[134:135], v[98:99]
	v_pk_mul_f32 v[98:99], v[136:137], v[98:99]
	v_add_f32_e32 v101, v101, v163
	v_add_f32_e32 v100, v100, v101
	v_add_f32_e32 v105, v2, v100
	v_mul_f32_e32 v100, 0xbfb8aa3b, v105
	v_exp_f32_e32 v100, v100
	v_add_f32_e32 v99, 0, v99
	v_add_f32_e32 v149, v98, v99
	v_pk_mul_f32 v[98:99], v[136:137], v[108:109]
	v_add_f32_e32 v100, 1.0, v100
	v_rcp_f32_e32 v104, v100
	v_add_f32_e32 v99, 0, v99
	v_add_f32_e32 v147, v98, v99
	v_and_b32_e32 v99, 0xffff0000, v94
	v_and_b32_e32 v98, 0xffff0000, v90
	v_mul_f32_e32 v159, v105, v104
	v_pk_mov_b32 v[104:105], v[98:99], v[106:107] op_sel:[1,0]
	v_pk_mul_f32 v[100:101], v[134:135], v[108:109]
	v_pk_mul_f32 v[106:107], v[10:11], v[104:105]
	v_add_f32_e32 v101, v101, v164
	v_add_f32_e32 v90, v107, v166
	v_add_f32_e32 v90, v106, v90
	v_add_f32_e32 v90, v3, v90
	v_mul_f32_e32 v94, 0xbfb8aa3b, v90
	v_exp_f32_e32 v94, v94
	v_add_f32_e32 v162, v100, v101
	v_pk_mul_f32 v[100:101], v[18:19], v[104:105]
	v_pk_mul_f32 v[104:105], v[18:19], v[98:99]
	v_add_f32_e32 v94, 1.0, v94
	v_rcp_f32_e32 v94, v94
	v_lshlrev_b32_e32 v107, 16, v95
	v_lshlrev_b32_e32 v106, 16, v91
	v_add_f32_e32 v101, 0, v101
	v_mul_f32_e32 v90, v90, v94
	v_add_f32_e32 v94, 0, v105
	v_add_f32_e32 v148, v104, v94
	v_pk_mov_b32 v[104:105], v[106:107], v[144:145] op_sel:[1,0]
	v_add_f32_e32 v150, v100, v101
	v_pk_mul_f32 v[144:145], v[130:131], v[104:105]
	v_pk_mul_f32 v[100:101], v[10:11], v[98:99]
	v_add_f32_e32 v94, v145, v169
	v_add_f32_e32 v94, v144, v94
	v_add_f32_e32 v94, v4, v94
	v_mul_f32_e32 v144, 0xbfb8aa3b, v94
	v_exp_f32_e32 v144, v144
	v_add_f32_e32 v101, v101, v167
	v_add_f32_e32 v163, v100, v101
	v_pk_mul_f32 v[100:101], v[132:133], v[104:105]
	v_add_f32_e32 v104, 1.0, v144
	v_rcp_f32_e32 v104, v104
	v_cvt_pk_bf16_f32 v90, v159, v90
	v_and_b32_e32 v95, 0xffff0000, v95
	v_add_f32_e32 v101, 0, v101
	v_mul_f32_e32 v159, v94, v104
	v_pk_mul_f32 v[104:105], v[132:133], v[106:107]
	v_add_f32_e32 v145, v100, v101
	v_add_f32_e32 v94, 0, v105
	v_add_f32_e32 v144, v104, v94
	v_and_b32_e32 v94, 0xffff0000, v91
	v_pk_mov_b32 v[104:105], v[94:95], v[142:143] op_sel:[1,0]
	v_pk_mul_f32 v[100:101], v[130:131], v[106:107]
	v_pk_mul_f32 v[142:143], v[12:13], v[104:105]
	v_add_f32_e32 v101, v101, v170
	v_add_f32_e32 v91, v143, v171
	v_add_f32_e32 v91, v142, v91
	v_add_f32_e32 v91, v5, v91
	v_mul_f32_e32 v142, 0xbfb8aa3b, v91
	v_exp_f32_e32 v142, v142
	v_add_f32_e32 v164, v100, v101
	v_pk_mul_f32 v[100:101], v[20:21], v[104:105]
	v_add_f32_e32 v104, 1.0, v142
	v_rcp_f32_e32 v104, v104
	v_add_f32_e32 v101, 0, v101
	v_add_f32_e32 v143, v100, v101
	v_pk_mul_f32 v[100:101], v[12:13], v[94:95]
	v_mul_f32_e32 v91, v91, v104
	v_pk_mul_f32 v[104:105], v[20:21], v[94:95]
	v_cvt_pk_bf16_f32 v91, v159, v91
	v_add_f32_e32 v101, v101, v172
	v_add_f32_e32 v105, 0, v105
	v_add_f32_e32 v142, v104, v105
	v_lshlrev_b32_e32 v105, 16, v96
	v_lshlrev_b32_e32 v104, 16, v92
	v_pk_mov_b32 v[138:139], v[104:105], v[138:139] op_sel:[1,0]
	v_add_f32_e32 v165, v100, v101
	v_pk_mul_f32 v[160:161], v[126:127], v[138:139]
	v_pk_mul_f32 v[100:101], v[128:129], v[138:139]
	v_add_f32_e32 v151, v161, v151
	v_add_f32_e32 v151, v160, v151
	v_add_f32_e32 v159, v6, v151
	v_mul_f32_e32 v151, 0xbfb8aa3b, v159
	v_exp_f32_e32 v151, v151
	v_add_f32_e32 v101, 0, v101
	v_pk_mul_f32 v[160:161], v[126:127], v[104:105]
	v_add_f32_e32 v138, 1.0, v151
	v_rcp_f32_e32 v138, v138
	v_add_f32_e32 v151, v100, v101
	v_pk_mul_f32 v[100:101], v[128:129], v[104:105]
	v_add_f32_e32 v139, v161, v158
	v_add_f32_e32 v101, 0, v101
	v_mul_f32_e32 v161, v159, v138
	v_add_f32_e32 v138, v100, v101
	v_and_b32_e32 v101, 0xffff0000, v96
	v_and_b32_e32 v100, 0xffff0000, v92
	v_pk_mov_b32 v[102:103], v[100:101], v[102:103] op_sel:[1,0]
	v_add_f32_e32 v166, v160, v139
	v_pk_mul_f32 v[158:159], v[14:15], v[102:103]
	v_pk_mul_f32 v[102:103], v[22:23], v[102:103]
	v_add_f32_e32 v92, v159, v152
	v_add_f32_e32 v92, v158, v92
	v_add_f32_e32 v92, v7, v92
	v_mul_f32_e32 v96, 0xbfb8aa3b, v92
	v_exp_f32_e32 v96, v96
	v_add_f32_e32 v103, 0, v103
	v_add_f32_e32 v152, v102, v103
	v_pk_mul_f32 v[102:103], v[22:23], v[100:101]
	v_add_f32_e32 v96, 1.0, v96
	v_rcp_f32_e32 v96, v96
	v_pk_mul_f32 v[158:159], v[14:15], v[100:101]
	v_mul_f32_e32 v92, v92, v96
	v_add_f32_e32 v96, 0, v103
	v_add_f32_e32 v139, v102, v96
	v_lshlrev_b32_e32 v103, 16, v97
	v_lshlrev_b32_e32 v102, 16, v93
	v_pk_mov_b32 v[112:113], v[102:103], v[112:113] op_sel:[1,0]
	v_cvt_pk_bf16_f32 v92, v161, v92
	v_add_f32_e32 v157, v159, v157
	v_pk_mul_f32 v[160:161], v[122:123], v[112:113]
	v_pk_mul_f32 v[112:113], v[124:125], v[112:113]
	v_add_f32_e32 v96, v161, v153
	v_add_f32_e32 v96, v160, v96
	v_add_f32_e32 v96, v8, v96
	v_mul_f32_e32 v153, 0xbfb8aa3b, v96
	v_exp_f32_e32 v153, v153
	v_add_f32_e32 v160, v158, v157
	v_add_f32_e32 v113, 0, v113
	v_and_b32_e32 v97, 0xffff0000, v97
	v_add_f32_e32 v153, 1.0, v153
	v_rcp_f32_e32 v157, v153
	v_add_f32_e32 v153, v112, v113
	v_pk_mul_f32 v[112:113], v[124:125], v[102:103]
	v_pk_mul_f32 v[158:159], v[122:123], v[102:103]
	v_mul_f32_e32 v161, v96, v157
	v_add_f32_e32 v96, 0, v113
	v_add_f32_e32 v112, v112, v96
	v_and_b32_e32 v96, 0xffff0000, v93
	v_pk_mov_b32 v[110:111], v[96:97], v[110:111] op_sel:[1,0]
	v_add_f32_e32 v159, v159, v156
	v_pk_mul_f32 v[156:157], v[16:17], v[110:111]
; __device__ __forceinline__ float siluf_(float x) { return x * sigmoidf_(x); }
; __device__ __forceinline__ void conv_pass(const Ctx& C_, int l) {
;     ...
;                 for (int k = 0; k < 4; ++k) { const int j = i - k;
;                     if (j >= 0 && j < 8) { float* o = oacc[j & 3];
;                         o[0] += cw[k][0].x * xv[0]; o[1] += cw[k][0].y * xv[1]; o[2] += cw[k][0].z * xv[2]; o[3] += cw[k][0].w * xv[3];
;                         o[4] += cw[k][1].x * xv[4]; o[5] += cw[k][1].y * xv[5]; o[6] += cw[k][1].z * xv[6]; o[7] += cw[k][1].w * xv[7]; } }
;                 if (i >= 3) {
;                     const int j = i - 3; const float* oa = oacc[j & 3];
;                     float o[8];
;                     o[0] = siluf_(oa[0] + cbias[0].x); o[1] = siluf_(oa[1] + cbias[0].y); o[2] = siluf_(oa[2] + cbias[0].z); o[3] = siluf_(oa[3] + cbias[0].w);
;                     o[4] = siluf_(oa[4] + cbias[1].x); o[5] = siluf_(oa[5] + cbias[1].y); o[6] = siluf_(oa[6] + cbias[1].z); o[7] = siluf_(oa[7] + cbias[1].w);
;                     *(u32x4*)(L_XBCC + (size_t)(m0 + j) * CONVD + ch) = pack8(o);
;                 }
	v_pk_mul_f32 v[110:111], v[24:25], v[110:111]
	v_add_f32_e32 v93, v157, v154
	v_add_f32_e32 v93, v156, v93
	v_add_f32_e32 v93, v9, v93
	v_mul_f32_e32 v113, 0xbfb8aa3b, v93
	v_exp_f32_e32 v113, v113
	v_add_f32_e32 v111, 0, v111
	v_add_f32_e32 v154, v110, v111
	v_pk_mul_f32 v[110:111], v[16:17], v[96:97]
	v_add_f32_e32 v113, 1.0, v113
	v_rcp_f32_e32 v113, v113
	v_add_f32_e32 v155, v111, v155
	v_pk_mul_f32 v[156:157], v[24:25], v[96:97]
	v_add_f32_e32 v158, v158, v159
	v_mul_f32_e32 v93, v93, v113
	v_cvt_pk_bf16_f32 v93, v161, v93
	global_store_dwordx4 v[140:141], v[90:93], off sc1
	v_add_f32_e32 v141, v5, v165
	v_add_f32_e32 v111, 0, v157
	v_add_f32_e32 v90, v110, v155
	v_add_f32_e32 v92, v3, v163
	v_add_f32_e32 v110, v4, v164
	v_mul_f32_e32 v93, 0xbfb8aa3b, v92
	v_mul_f32_e32 v140, 0xbfb8aa3b, v110
	v_exp_f32_e32 v93, v93
	v_exp_f32_e32 v140, v140
	v_add_f32_e32 v113, v2, v162
	v_mul_f32_e32 v155, 0xbfb8aa3b, v141
	v_add_f32_e32 v93, 1.0, v93
	v_add_f32_e32 v140, 1.0, v140
	v_add_f32_e32 v111, v156, v111
	v_mul_f32_e32 v156, 0xbfb8aa3b, v113
	v_rcp_f32_e32 v93, v93
	v_rcp_f32_e32 v140, v140
	v_exp_f32_e32 v155, v155
	v_exp_f32_e32 v156, v156
	v_mul_f32_e32 v92, v92, v93
	v_mul_f32_e32 v93, v110, v140
	v_add_f32_e32 v110, 1.0, v155
	v_add_f32_e32 v155, v7, v160
	v_add_f32_e32 v91, 1.0, v156
	v_mul_f32_e32 v156, 0xbfb8aa3b, v155
	v_rcp_f32_e32 v91, v91
	v_rcp_f32_e32 v110, v110
	v_exp_f32_e32 v156, v156
	v_add_f32_e32 v90, v9, v90
	v_mul_f32_e32 v91, v113, v91
	v_add_f32_e32 v113, v6, v166
	v_mul_f32_e32 v110, v141, v110
	v_add_f32_e32 v141, 1.0, v156
	v_add_f32_e32 v156, v8, v158
	v_mul_f32_e32 v140, 0xbfb8aa3b, v113
	v_mul_f32_e32 v157, 0xbfb8aa3b, v156
	v_mul_f32_e32 v158, 0xbfb8aa3b, v90
	v_exp_f32_e32 v140, v140
	v_exp_f32_e32 v157, v157
	v_exp_f32_e32 v158, v158
	v_rcp_f32_e32 v141, v141
	v_add_f32_e32 v140, 1.0, v140
	v_add_f32_e32 v157, 1.0, v157
	v_add_f32_e32 v158, 1.0, v158
	v_rcp_f32_e32 v140, v140
	v_rcp_f32_e32 v157, v157
	v_rcp_f32_e32 v158, v158
	v_mul_f32_e32 v113, v113, v140
	v_mul_f32_e32 v140, v155, v141
	v_mul_f32_e32 v141, v156, v157
	v_mul_f32_e32 v155, v90, v158
	v_cvt_pk_bf16_f32 v90, v91, v92
	v_cvt_pk_bf16_f32 v91, v93, v110
	v_add_u32_e32 v110, -5, v115
	v_cvt_pk_bf16_f32 v92, v113, v140
	v_cvt_pk_bf16_f32 v93, v141, v155
	v_mad_i64_i32 v[140:141], s[0:1], v110, s2, v[120:121]
	global_store_dwordx4 v[140:141], v[90:93], off sc1
	v_add_u32_e32 v110, -4, v115
	s_waitcnt vmcnt(7)
	v_lshlrev_b32_e32 v91, 16, v86
	s_waitcnt vmcnt(6)
	v_lshlrev_b32_e32 v90, 16, v82
	v_pk_mov_b32 v[92:93], v[90:91], v[108:109] op_sel:[1,0]
	v_pk_mul_f32 v[156:157], v[134:135], v[90:91]
	v_pk_mul_f32 v[108:109], v[134:135], v[92:93]
	v_pk_mul_f32 v[92:93], v[136:137], v[92:93]
	v_add_f32_e32 v109, v109, v149
	v_add_f32_e32 v108, v108, v109
	v_add_f32_e32 v113, v2, v108
	v_mul_f32_e32 v108, 0xbfb8aa3b, v113
	v_exp_f32_e32 v140, v108
	v_mad_i64_i32 v[108:109], s[0:1], v110, s2, v[120:121]
	v_add_f32_e32 v93, 0, v93
	v_add_f32_e32 v110, 1.0, v140
	v_rcp_f32_e32 v110, v110
	v_add_f32_e32 v140, v92, v93
	v_pk_mul_f32 v[92:93], v[136:137], v[90:91]
	v_add_f32_e32 v141, v157, v147
	v_add_f32_e32 v93, 0, v93
	v_mul_f32_e32 v147, v113, v110
	v_add_f32_e32 v110, v92, v93
	v_and_b32_e32 v93, 0xffff0000, v86
	v_and_b32_e32 v92, 0xffff0000, v82
	v_pk_mov_b32 v[98:99], v[92:93], v[98:99] op_sel:[1,0]
	v_add_f32_e32 v155, v156, v141
	v_pk_mul_f32 v[158:159], v[10:11], v[98:99]
	v_pk_mul_f32 v[98:99], v[18:19], v[98:99]
	v_add_f32_e32 v82, v159, v150
	v_add_f32_e32 v82, v158, v82
	v_add_f32_e32 v82, v3, v82
	v_mul_f32_e32 v86, 0xbfb8aa3b, v82
	v_exp_f32_e32 v86, v86
	v_add_f32_e32 v99, 0, v99
	v_add_f32_e32 v141, v98, v99
	v_pk_mul_f32 v[98:99], v[18:19], v[92:93]
	v_add_f32_e32 v86, 1.0, v86
	v_rcp_f32_e32 v86, v86
	v_pk_mul_f32 v[156:157], v[10:11], v[92:93]
	v_mul_f32_e32 v82, v82, v86
	v_add_f32_e32 v86, 0, v99
	v_add_f32_e32 v113, v98, v86
	v_lshlrev_b32_e32 v99, 16, v87
	v_lshlrev_b32_e32 v98, 16, v83
	v_pk_mov_b32 v[106:107], v[98:99], v[106:107] op_sel:[1,0]
	v_add_f32_e32 v150, v157, v148
	v_pk_mul_f32 v[148:149], v[130:131], v[106:107]
	v_cvt_pk_bf16_f32 v82, v147, v82
	v_pk_mul_f32 v[106:107], v[132:133], v[106:107]
	v_add_f32_e32 v86, v149, v145
	v_add_f32_e32 v86, v148, v86
	v_add_f32_e32 v86, v4, v86
	v_mul_f32_e32 v145, 0xbfb8aa3b, v86
	v_exp_f32_e32 v145, v145
	v_add_f32_e32 v107, 0, v107
	v_and_b32_e32 v87, 0xffff0000, v87
	v_add_f32_e32 v158, v156, v150
	v_add_f32_e32 v145, 1.0, v145
	v_rcp_f32_e32 v147, v145
	v_add_f32_e32 v145, v106, v107
	v_pk_mul_f32 v[106:107], v[132:133], v[98:99]
	v_pk_mul_f32 v[148:149], v[130:131], v[98:99]
	v_mul_f32_e32 v147, v86, v147
	v_add_f32_e32 v86, 0, v107
	v_add_f32_e32 v106, v106, v86
	v_and_b32_e32 v86, 0xffff0000, v83
	v_pk_mov_b32 v[94:95], v[86:87], v[94:95] op_sel:[1,0]
	v_add_f32_e32 v144, v149, v144
	v_pk_mul_f32 v[156:157], v[12:13], v[94:95]
	v_pk_mul_f32 v[94:95], v[20:21], v[94:95]
	v_add_f32_e32 v83, v157, v143
	v_add_f32_e32 v83, v156, v83
	v_add_f32_e32 v83, v5, v83
	v_mul_f32_e32 v107, 0xbfb8aa3b, v83
	v_exp_f32_e32 v107, v107
	v_add_f32_e32 v95, 0, v95
	v_add_f32_e32 v143, v94, v95
	v_pk_mul_f32 v[94:95], v[20:21], v[86:87]
	v_add_f32_e32 v107, 1.0, v107
	v_rcp_f32_e32 v107, v107
	v_add_f32_e32 v95, 0, v95
	v_add_f32_e32 v159, v148, v144
	v_pk_mul_f32 v[148:149], v[12:13], v[86:87]
	v_mul_f32_e32 v83, v83, v107
	v_add_f32_e32 v107, v94, v95
	v_lshlrev_b32_e32 v95, 16, v88
	v_lshlrev_b32_e32 v94, 16, v84
	v_pk_mov_b32 v[104:105], v[94:95], v[104:105] op_sel:[1,0]
	v_cvt_pk_bf16_f32 v83, v147, v83
	v_add_f32_e32 v142, v149, v142
	v_pk_mul_f32 v[156:157], v[126:127], v[104:105]
; __device__ __forceinline__ float siluf_(float x) { return x * sigmoidf_(x); }
; __device__ __forceinline__ void conv_pass(const Ctx& C_, int l) {
;     ...
;                 for (int k = 0; k < 4; ++k) { const int j = i - k;
;                     if (j >= 0 && j < 8) { float* o = oacc[j & 3];
;                         o[0] += cw[k][0].x * xv[0]; o[1] += cw[k][0].y * xv[1]; o[2] += cw[k][0].z * xv[2]; o[3] += cw[k][0].w * xv[3];
;                         o[4] += cw[k][1].x * xv[4]; o[5] += cw[k][1].y * xv[5]; o[6] += cw[k][1].z * xv[6]; o[7] += cw[k][1].w * xv[7]; } }
;                 if (i >= 3) {
;                     const int j = i - 3; const float* oa = oacc[j & 3];
;                     float o[8];
;                     o[0] = siluf_(oa[0] + cbias[0].x); o[1] = siluf_(oa[1] + cbias[0].y); o[2] = siluf_(oa[2] + cbias[0].z); o[3] = siluf_(oa[3] + cbias[0].w);
;                     o[4] = siluf_(oa[4] + cbias[1].x); o[5] = siluf_(oa[5] + cbias[1].y); o[6] = siluf_(oa[6] + cbias[1].z); o[7] = siluf_(oa[7] + cbias[1].w);
;                     *(u32x4*)(L_XBCC + (size_t)(m0 + j) * CONVD + ch) = pack8(o);
;                 }
	v_pk_mul_f32 v[104:105], v[128:129], v[104:105]
	v_add_f32_e32 v144, v157, v151
	v_add_f32_e32 v144, v156, v144
	v_add_f32_e32 v144, v6, v144
	v_mul_f32_e32 v147, 0xbfb8aa3b, v144
	v_exp_f32_e32 v147, v147
	v_add_f32_e32 v156, v148, v142
	v_add_f32_e32 v105, 0, v105
	v_pk_mul_f32 v[148:149], v[126:127], v[94:95]
	v_add_f32_e32 v142, 1.0, v147
	v_rcp_f32_e32 v147, v142
	v_add_f32_e32 v142, v104, v105
	v_pk_mul_f32 v[104:105], v[128:129], v[94:95]
	v_add_f32_e32 v149, v149, v138
	v_add_f32_e32 v105, 0, v105
	v_add_f32_e32 v138, v104, v105
	v_and_b32_e32 v105, 0xffff0000, v88
	v_and_b32_e32 v104, 0xffff0000, v84
	v_pk_mov_b32 v[100:101], v[104:105], v[100:101] op_sel:[1,0]
	v_mul_f32_e32 v147, v144, v147
	v_pk_mul_f32 v[150:151], v[14:15], v[100:101]
	v_pk_mul_f32 v[100:101], v[22:23], v[100:101]
	v_add_f32_e32 v84, v151, v152
	v_add_f32_e32 v84, v150, v84
	v_add_f32_e32 v84, v7, v84
	v_mul_f32_e32 v88, 0xbfb8aa3b, v84
	v_exp_f32_e32 v88, v88
	v_add_f32_e32 v101, 0, v101
	v_add_f32_e32 v144, v100, v101
	v_pk_mul_f32 v[100:101], v[22:23], v[104:105]
	v_add_f32_e32 v88, 1.0, v88
	v_rcp_f32_e32 v88, v88
	v_add_f32_e32 v152, v148, v149
	v_pk_mul_f32 v[148:149], v[14:15], v[104:105]
	v_mul_f32_e32 v84, v84, v88
	v_add_f32_e32 v88, 0, v101
	v_add_f32_e32 v149, v149, v139
	v_add_f32_e32 v139, v100, v88
	v_lshlrev_b32_e32 v101, 16, v89
	v_lshlrev_b32_e32 v100, 16, v85
	v_pk_mov_b32 v[102:103], v[100:101], v[102:103] op_sel:[1,0]
	v_cvt_pk_bf16_f32 v84, v147, v84
	v_and_b32_e32 v89, 0xffff0000, v89
	v_pk_mul_f32 v[150:151], v[122:123], v[102:103]
	v_pk_mul_f32 v[102:103], v[124:125], v[102:103]
	v_add_f32_e32 v88, v151, v153
	v_add_f32_e32 v88, v150, v88
	v_add_f32_e32 v88, v8, v88
	v_mul_f32_e32 v147, 0xbfb8aa3b, v88
	v_exp_f32_e32 v147, v147
	v_add_f32_e32 v103, 0, v103
	v_add_f32_e32 v153, v148, v149
	v_pk_mul_f32 v[148:149], v[122:123], v[100:101]
	v_add_f32_e32 v147, 1.0, v147
	v_rcp_f32_e32 v150, v147
	v_add_f32_e32 v147, v102, v103
	v_pk_mul_f32 v[102:103], v[124:125], v[100:101]
	v_add_f32_e32 v112, v149, v112
	v_mul_f32_e32 v157, v88, v150
	v_add_f32_e32 v88, 0, v103
	v_add_f32_e32 v102, v102, v88
	v_and_b32_e32 v88, 0xffff0000, v85
	v_pk_mov_b32 v[96:97], v[88:89], v[96:97] op_sel:[1,0]
	s_nop 0
	v_pk_mul_f32 v[150:151], v[16:17], v[96:97]
	v_pk_mul_f32 v[96:97], v[24:25], v[96:97]
	v_add_f32_e32 v85, v151, v154
	v_add_f32_e32 v85, v150, v85
	v_add_f32_e32 v85, v9, v85
	v_mul_f32_e32 v103, 0xbfb8aa3b, v85
	v_exp_f32_e32 v103, v103
	v_add_f32_e32 v97, 0, v97
	v_add_f32_e32 v150, v148, v112
	v_add_f32_e32 v112, v96, v97
	v_add_f32_e32 v103, 1.0, v103
	v_rcp_f32_e32 v103, v103
	v_pk_mul_f32 v[96:97], v[16:17], v[88:89]
	v_pk_mul_f32 v[148:149], v[24:25], v[88:89]
	v_add_f32_e32 v97, v97, v111
	v_mul_f32_e32 v85, v85, v103
	v_add_f32_e32 v103, 0, v149
	v_add_f32_e32 v111, v2, v155
	v_cvt_pk_bf16_f32 v85, v157, v85
	global_store_dwordx4 v[108:109], v[82:85], off sc1
	v_add_f32_e32 v103, v148, v103
	v_mul_f32_e32 v148, 0xbfb8aa3b, v111
	v_add_f32_e32 v82, v96, v97
	v_add_f32_e32 v84, v3, v158
	v_add_f32_e32 v96, v4, v159
	v_mul_f32_e32 v85, 0xbfb8aa3b, v84
	v_mul_f32_e32 v97, 0xbfb8aa3b, v96
	v_exp_f32_e32 v148, v148
	v_exp_f32_e32 v85, v85
	v_exp_f32_e32 v97, v97
	v_add_f32_e32 v108, v5, v156
	v_add_f32_e32 v83, 1.0, v148
	v_add_f32_e32 v85, 1.0, v85
	v_add_f32_e32 v97, 1.0, v97
	v_rcp_f32_e32 v83, v83
	v_rcp_f32_e32 v85, v85
	v_rcp_f32_e32 v97, v97
	v_mul_f32_e32 v109, 0xbfb8aa3b, v108
	v_exp_f32_e32 v109, v109
	v_mul_f32_e32 v83, v111, v83
	v_mul_f32_e32 v84, v84, v85
	v_mul_f32_e32 v85, v96, v97
	v_add_f32_e32 v97, v6, v152
	v_add_f32_e32 v111, v7, v153
	v_add_f32_e32 v96, 1.0, v109
	v_mul_f32_e32 v109, 0xbfb8aa3b, v97
	v_mul_f32_e32 v148, 0xbfb8aa3b, v111
	v_rcp_f32_e32 v96, v96
	v_exp_f32_e32 v109, v109
	v_exp_f32_e32 v148, v148
	v_add_f32_e32 v82, v9, v82
	v_mul_f32_e32 v96, v108, v96
	v_add_f32_e32 v108, 1.0, v109
	v_add_f32_e32 v109, 1.0, v148
	v_add_f32_e32 v148, v8, v150
	v_mul_f32_e32 v150, 0xbfb8aa3b, v82
	v_exp_f32_e32 v150, v150
	v_mul_f32_e32 v149, 0xbfb8aa3b, v148
	v_exp_f32_e32 v149, v149
	v_rcp_f32_e32 v108, v108
	v_add_f32_e32 v150, 1.0, v150
	v_rcp_f32_e32 v109, v109
	v_rcp_f32_e32 v150, v150
	v_add_f32_e32 v149, 1.0, v149
	v_rcp_f32_e32 v149, v149
	v_mul_f32_e32 v97, v97, v108
	v_mul_f32_e32 v108, v111, v109
	v_mul_f32_e32 v111, v82, v150
	v_cvt_pk_bf16_f32 v82, v83, v84
	v_cvt_pk_bf16_f32 v83, v85, v96
	v_add_u32_e32 v96, -3, v115
	v_cvt_pk_bf16_f32 v84, v97, v108
	v_mad_i64_i32 v[96:97], s[0:1], v96, s2, v[120:121]
	v_mul_f32_e32 v109, v148, v149
	v_cvt_pk_bf16_f32 v85, v109, v111
	global_store_dwordx4 v[96:97], v[82:85], off sc1
	v_add_u32_e32 v96, -2, v115
	v_mad_i64_i32 v[96:97], s[0:1], v96, s2, v[120:121]
	s_waitcnt vmcnt(7)
	v_lshlrev_b32_e32 v83, 16, v78
	s_waitcnt vmcnt(6)
; __device__ __forceinline__ float siluf_(float x) { return x * sigmoidf_(x); }
; __device__ __forceinline__ void conv_pass(const Ctx& C_, int l) {
;     ...
;                 for (int k = 0; k < 4; ++k) { const int j = i - k;
;                     if (j >= 0 && j < 8) { float* o = oacc[j & 3];
;                         o[0] += cw[k][0].x * xv[0]; o[1] += cw[k][0].y * xv[1]; o[2] += cw[k][0].z * xv[2]; o[3] += cw[k][0].w * xv[3];
;                         o[4] += cw[k][1].x * xv[4]; o[5] += cw[k][1].y * xv[5]; o[6] += cw[k][1].z * xv[6]; o[7] += cw[k][1].w * xv[7]; } }
;                 if (i >= 3) {
;                     const int j = i - 3; const float* oa = oacc[j & 3];
;                     float o[8];
;                     o[0] = siluf_(oa[0] + cbias[0].x); o[1] = siluf_(oa[1] + cbias[0].y); o[2] = siluf_(oa[2] + cbias[0].z); o[3] = siluf_(oa[3] + cbias[0].w);
;                     o[4] = siluf_(oa[4] + cbias[1].x); o[5] = siluf_(oa[5] + cbias[1].y); o[6] = siluf_(oa[6] + cbias[1].z); o[7] = siluf_(oa[7] + cbias[1].w);
;                     *(u32x4*)(L_XBCC + (size_t)(m0 + j) * CONVD + ch) = pack8(o);
;                 }
	v_lshlrev_b32_e32 v82, 16, v74
	v_pk_mov_b32 v[84:85], v[82:83], v[90:91] op_sel:[1,0]
	s_nop 0
	v_pk_mul_f32 v[90:91], v[134:135], v[84:85]
	v_pk_mul_f32 v[84:85], v[136:137], v[84:85]
	v_add_f32_e32 v91, v91, v140
	v_add_f32_e32 v90, v90, v91
	v_add_f32_e32 v109, v2, v90
	v_mul_f32_e32 v90, 0xbfb8aa3b, v109
	v_exp_f32_e32 v90, v90
	v_add_f32_e32 v85, 0, v85
	v_add_f32_e32 v108, v84, v85
	v_and_b32_e32 v85, 0xffff0000, v78
	v_add_f32_e32 v90, 1.0, v90
	v_rcp_f32_e32 v111, v90
	v_and_b32_e32 v84, 0xffff0000, v74
	v_pk_mul_f32 v[90:91], v[134:135], v[82:83]
	v_pk_mov_b32 v[92:93], v[84:85], v[92:93] op_sel:[1,0]
	v_add_f32_e32 v83, v91, v110
	v_mul_f32_e32 v109, v109, v111
	v_pk_mul_f32 v[110:111], v[10:11], v[92:93]
	v_add_f32_e32 v140, v90, v83
	v_add_f32_e32 v74, v111, v141
	v_add_f32_e32 v74, v110, v74
	v_add_f32_e32 v74, v3, v74
	v_mul_f32_e32 v78, 0xbfb8aa3b, v74
	v_exp_f32_e32 v78, v78
	v_pk_mul_f32 v[90:91], v[18:19], v[92:93]
	v_pk_mul_f32 v[92:93], v[10:11], v[84:85]
	v_add_f32_e32 v83, 0, v91
	v_add_f32_e32 v78, 1.0, v78
	v_rcp_f32_e32 v78, v78
	v_add_f32_e32 v83, v90, v83
	v_lshlrev_b32_e32 v91, 16, v79
	v_lshlrev_b32_e32 v90, 16, v75
	v_pk_mov_b32 v[98:99], v[90:91], v[98:99] op_sel:[1,0]
	v_mul_f32_e32 v74, v74, v78
	v_pk_mul_f32 v[110:111], v[130:131], v[98:99]
	v_add_f32_e32 v85, v93, v113
	v_add_f32_e32 v78, v111, v145
	v_add_f32_e32 v78, v110, v78
	v_add_f32_e32 v78, v4, v78
	v_mul_f32_e32 v93, 0xbfb8aa3b, v78
	v_cvt_pk_bf16_f32 v74, v109, v74
	v_exp_f32_e32 v109, v93
	v_add_f32_e32 v110, v92, v85
	v_pk_mul_f32 v[92:93], v[132:133], v[98:99]
	v_and_b32_e32 v79, 0xffff0000, v79
	v_add_f32_e32 v85, 0, v93
	v_add_f32_e32 v93, 1.0, v109
	v_rcp_f32_e32 v98, v93
	v_add_f32_e32 v85, v92, v85
	v_pk_mul_f32 v[92:93], v[130:131], v[90:91]
	s_nop 0
	v_add_f32_e32 v91, v93, v106
	v_mul_f32_e32 v106, v78, v98
	v_and_b32_e32 v78, 0xffff0000, v75
	v_pk_mov_b32 v[86:87], v[78:79], v[86:87] op_sel:[1,0]
	v_add_f32_e32 v91, v92, v91
	v_pk_mul_f32 v[98:99], v[12:13], v[86:87]
	v_pk_mul_f32 v[86:87], v[20:21], v[86:87]
	v_add_f32_e32 v75, v99, v143
	v_add_f32_e32 v75, v98, v75
	v_add_f32_e32 v75, v5, v75
	v_mul_f32_e32 v93, 0xbfb8aa3b, v75
	v_exp_f32_e32 v93, v93
	v_add_f32_e32 v87, 0, v87
	v_add_f32_e32 v109, v86, v87
	v_lshlrev_b32_e32 v87, 16, v80
	v_add_f32_e32 v92, 1.0, v93
	v_rcp_f32_e32 v98, v92
	v_lshlrev_b32_e32 v86, 16, v76
	v_pk_mov_b32 v[94:95], v[86:87], v[94:95] op_sel:[1,0]
	v_pk_mul_f32 v[92:93], v[12:13], v[78:79]
	v_mul_f32_e32 v75, v75, v98
	v_pk_mul_f32 v[98:99], v[126:127], v[94:95]
	v_add_f32_e32 v79, v93, v107
	v_add_f32_e32 v93, v99, v142
	v_add_f32_e32 v93, v98, v93
	v_add_f32_e32 v98, v6, v93
	v_mul_f32_e32 v93, 0xbfb8aa3b, v98
	v_exp_f32_e32 v99, v93
	v_add_f32_e32 v79, v92, v79
	v_pk_mul_f32 v[92:93], v[128:129], v[94:95]
	v_cvt_pk_bf16_f32 v75, v106, v75
	v_add_f32_e32 v94, 1.0, v99
	v_rcp_f32_e32 v99, v94
	v_add_f32_e32 v93, 0, v93
	v_add_f32_e32 v106, v92, v93
	v_and_b32_e32 v93, 0xffff0000, v80
	v_and_b32_e32 v92, 0xffff0000, v76
	v_mul_f32_e32 v107, v98, v99
	v_pk_mov_b32 v[98:99], v[92:93], v[104:105] op_sel:[1,0]
	v_pk_mul_f32 v[94:95], v[126:127], v[86:87]
	v_pk_mul_f32 v[104:105], v[14:15], v[98:99]
	v_add_f32_e32 v87, v95, v138
	v_add_f32_e32 v76, v105, v144
	v_add_f32_e32 v76, v104, v76
	v_add_f32_e32 v76, v7, v76
	v_mul_f32_e32 v80, 0xbfb8aa3b, v76
	v_exp_f32_e32 v80, v80
	v_add_f32_e32 v87, v94, v87
	v_pk_mul_f32 v[94:95], v[22:23], v[98:99]
	v_pk_mul_f32 v[98:99], v[14:15], v[92:93]
	v_add_f32_e32 v80, 1.0, v80
	v_add_f32_e32 v95, 0, v95
	v_rcp_f32_e32 v80, v80
	v_add_f32_e32 v111, v94, v95
	v_lshlrev_b32_e32 v95, 16, v81
	v_lshlrev_b32_e32 v94, 16, v77
	v_pk_mov_b32 v[100:101], v[94:95], v[100:101] op_sel:[1,0]
	v_mul_f32_e32 v76, v76, v80
	v_pk_mul_f32 v[104:105], v[122:123], v[100:101]
	v_add_f32_e32 v93, v99, v139
	v_add_f32_e32 v80, v105, v147
	v_add_f32_e32 v80, v104, v80
	v_add_f32_e32 v80, v8, v80
	v_mul_f32_e32 v99, 0xbfb8aa3b, v80
	v_exp_f32_e32 v104, v99
	v_add_f32_e32 v93, v98, v93
	v_pk_mul_f32 v[98:99], v[124:125], v[100:101]
	v_and_b32_e32 v81, 0xffff0000, v81
	v_add_f32_e32 v100, 1.0, v104
	v_rcp_f32_e32 v100, v100
	v_add_f32_e32 v99, 0, v99
	v_add_f32_e32 v104, v98, v99
	v_pk_mul_f32 v[98:99], v[122:123], v[94:95]
	v_cvt_pk_bf16_f32 v76, v107, v76
	v_add_f32_e32 v79, v5, v79
	v_add_f32_e32 v95, v99, v102
	v_mul_f32_e32 v99, v80, v100
	v_and_b32_e32 v80, 0xffff0000, v77
	v_pk_mov_b32 v[88:89], v[80:81], v[88:89] op_sel:[1,0]
	v_add_f32_e32 v95, v98, v95
	v_pk_mul_f32 v[100:101], v[16:17], v[88:89]
	v_pk_mul_f32 v[88:89], v[24:25], v[88:89]
	v_add_f32_e32 v77, v101, v112
	v_add_f32_e32 v77, v100, v77
	v_add_f32_e32 v77, v9, v77
	v_mul_f32_e32 v100, 0xbfb8aa3b, v77
	v_exp_f32_e32 v100, v100
	v_add_f32_e32 v89, 0, v89
	v_add_f32_e32 v102, v88, v89
	v_pk_mul_f32 v[88:89], v[16:17], v[80:81]
	v_add_f32_e32 v98, 1.0, v100
	v_rcp_f32_e32 v98, v98
	v_add_f32_e32 v81, v89, v103
	v_add_f32_e32 v89, v2, v140
	v_add_f32_e32 v87, v6, v87
	v_mul_f32_e32 v77, v77, v98
	v_mul_f32_e32 v98, 0xbfb8aa3b, v89
	v_cvt_pk_bf16_f32 v77, v99, v77
	global_store_dwordx4 v[96:97], v[74:77], off sc1
	v_exp_f32_e32 v98, v98
	s_waitcnt vmcnt(6)
; __device__ __forceinline__ float siluf_(float x) { return x * sigmoidf_(x); }
; __device__ __forceinline__ void conv_pass(const Ctx& C_, int l) {
;     ...
;                 if (i >= 3) {
;                     const int j = i - 3; const float* oa = oacc[j & 3];
;                     float o[8];
;                     o[0] = siluf_(oa[0] + cbias[0].x); o[1] = siluf_(oa[1] + cbias[0].y); o[2] = siluf_(oa[2] + cbias[0].z); o[3] = siluf_(oa[3] + cbias[0].w);
;                     o[4] = siluf_(oa[4] + cbias[1].x); o[5] = siluf_(oa[5] + cbias[1].y); o[6] = siluf_(oa[6] + cbias[1].z); o[7] = siluf_(oa[7] + cbias[1].w);
;                     *(u32x4*)(L_XBCC + (size_t)(m0 + j) * CONVD + ch) = pack8(o);
;                 }
;             }
;             if (more) {
; #pragma unroll
;                 for (int i = 0; i < 11; ++i) raw[i] = nraw[i];
;             }
	v_lshlrev_b32_e32 v96, 16, v52
	v_add_f32_e32 v74, v88, v81
	v_add_f32_e32 v76, v3, v110
	v_add_f32_e32 v81, v4, v91
	v_mul_f32_e32 v77, 0xbfb8aa3b, v76
	v_mul_f32_e32 v88, 0xbfb8aa3b, v81
	v_exp_f32_e32 v77, v77
	v_exp_f32_e32 v88, v88
	v_add_f32_e32 v75, 1.0, v98
	v_rcp_f32_e32 v75, v75
	v_add_f32_e32 v77, 1.0, v77
	v_add_f32_e32 v88, 1.0, v88
	v_mul_f32_e32 v91, 0xbfb8aa3b, v79
	v_rcp_f32_e32 v77, v77
	v_rcp_f32_e32 v88, v88
	v_exp_f32_e32 v91, v91
	v_mul_f32_e32 v75, v89, v75
	v_add_f32_e32 v89, v7, v93
	v_mul_f32_e32 v76, v76, v77
	v_mul_f32_e32 v77, v81, v88
	v_add_f32_e32 v81, 1.0, v91
	v_mul_f32_e32 v88, 0xbfb8aa3b, v87
	v_mul_f32_e32 v91, 0xbfb8aa3b, v89
	v_rcp_f32_e32 v81, v81
	v_exp_f32_e32 v88, v88
	v_exp_f32_e32 v91, v91
	v_add_f32_e32 v74, v9, v74
	v_mul_f32_e32 v79, v79, v81
	v_add_f32_e32 v81, 1.0, v88
	v_add_f32_e32 v88, 1.0, v91
	v_add_f32_e32 v91, v8, v95
	v_mul_f32_e32 v93, 0xbfb8aa3b, v91
	v_mul_f32_e32 v95, 0xbfb8aa3b, v74
	v_exp_f32_e32 v93, v93
	v_exp_f32_e32 v95, v95
	v_rcp_f32_e32 v81, v81
	v_rcp_f32_e32 v88, v88
	v_add_f32_e32 v93, 1.0, v93
	v_add_f32_e32 v95, 1.0, v95
	v_rcp_f32_e32 v93, v93
	v_rcp_f32_e32 v95, v95
	v_mul_f32_e32 v81, v87, v81
	v_mul_f32_e32 v87, v89, v88
	v_mul_f32_e32 v88, v91, v93
	v_mul_f32_e32 v89, v74, v95
	v_cvt_pk_bf16_f32 v74, v75, v76
	v_cvt_pk_bf16_f32 v75, v77, v79
	v_add_u32_e32 v79, -1, v115
	v_cvt_pk_bf16_f32 v77, v88, v89
	v_mad_i64_i32 v[88:89], s[0:1], v79, s2, v[120:121]
	v_cvt_pk_bf16_f32 v76, v81, v87
	global_store_dwordx4 v[88:89], v[74:77], off sc1
	v_and_b32_e32 v88, 0xffff0000, v51
	v_mov_b32_e32 v89, v78
	v_lshlrev_b32_e32 v74, 16, v50
	v_mov_b32_e32 v75, v82
	v_pk_mul_f32 v[74:75], v[134:135], v[74:75]
	v_lshlrev_b32_e32 v76, 16, v51
	v_add_f32_e32 v51, v75, v108
	v_and_b32_e32 v50, 0xffff0000, v50
	v_add_f32_e32 v74, v74, v51
	v_mov_b32_e32 v51, v84
	v_pk_mul_f32 v[50:51], v[10:11], v[50:51]
	v_mov_b32_e32 v77, v90
	v_add_f32_e32 v51, v51, v83
	v_add_f32_e32 v75, v50, v51
	v_pk_mul_f32 v[50:51], v[130:131], v[76:77]
	v_mov_b32_e32 v97, v86
	v_add_f32_e32 v51, v51, v85
	v_add_f32_e32 v76, v50, v51
	v_pk_mul_f32 v[50:51], v[12:13], v[88:89]
	v_and_b32_e32 v52, 0xffff0000, v52
	v_add_f32_e32 v51, v51, v109
	v_add_f32_e32 v77, v50, v51
	v_pk_mul_f32 v[50:51], v[126:127], v[96:97]
	v_lshlrev_b32_e32 v98, 16, v53
	v_and_b32_e32 v100, 0xffff0000, v53
	v_add_f32_e32 v51, v51, v106
	v_mov_b32_e32 v53, v92
	v_add_f32_e32 v78, v50, v51
	v_pk_mul_f32 v[50:51], v[14:15], v[52:53]
	v_mov_b32_e32 v99, v94
	v_add_f32_e32 v51, v51, v111
	v_add_f32_e32 v52, v50, v51
	v_pk_mul_f32 v[50:51], v[122:123], v[98:99]
	v_add_f32_e32 v74, v2, v74
	v_add_f32_e32 v51, v51, v104
	v_add_f32_e32 v53, v50, v51
	v_mul_f32_e32 v50, 0xbfb8aa3b, v74
	v_exp_f32_e32 v79, v50
	v_mov_b32_e32 v101, v80
	v_pk_mul_f32 v[50:51], v[16:17], v[100:101]
	v_add_f32_e32 v75, v3, v75
	v_add_f32_e32 v51, v51, v102
	v_add_f32_e32 v76, v4, v76
	v_add_f32_e32 v50, v50, v51
	v_add_f32_e32 v51, 1.0, v79
	v_mul_f32_e32 v79, 0xbfb8aa3b, v75
	v_mul_f32_e32 v80, 0xbfb8aa3b, v76
	v_exp_f32_e32 v79, v79
	v_exp_f32_e32 v80, v80
	v_add_f32_e32 v77, v5, v77
	v_mul_f32_e32 v81, 0xbfb8aa3b, v77
	v_add_f32_e32 v79, 1.0, v79
	v_add_f32_e32 v80, 1.0, v80
	v_rcp_f32_e32 v51, v51
	v_rcp_f32_e32 v79, v79
	v_rcp_f32_e32 v80, v80
	v_exp_f32_e32 v81, v81
	v_add_f32_e32 v78, v6, v78
	v_add_f32_e32 v52, v7, v52
	v_mul_f32_e32 v51, v74, v51
	v_mul_f32_e32 v74, v75, v79
	v_mul_f32_e32 v75, v76, v80
	v_add_f32_e32 v76, 1.0, v81
	v_mul_f32_e32 v79, 0xbfb8aa3b, v78
	v_mul_f32_e32 v80, 0xbfb8aa3b, v52
	v_rcp_f32_e32 v76, v76
	v_exp_f32_e32 v79, v79
	v_exp_f32_e32 v80, v80
	v_add_f32_e32 v53, v8, v53
	v_mul_f32_e32 v76, v77, v76
	v_add_f32_e32 v77, 1.0, v79
	v_add_f32_e32 v79, 1.0, v80
	v_mul_f32_e32 v80, 0xbfb8aa3b, v53
	v_add_f32_e32 v50, v9, v50
	v_exp_f32_e32 v80, v80
	v_mul_f32_e32 v81, 0xbfb8aa3b, v50
	v_exp_f32_e32 v81, v81
	v_rcp_f32_e32 v79, v79
	v_add_f32_e32 v80, 1.0, v80
	v_rcp_f32_e32 v80, v80
	v_add_f32_e32 v81, 1.0, v81
	v_rcp_f32_e32 v77, v77
	v_rcp_f32_e32 v81, v81
	v_mul_f32_e32 v52, v52, v79
	v_mul_f32_e32 v53, v53, v80
	v_mul_f32_e32 v77, v78, v77
	v_mul_f32_e32 v78, v50, v81
	v_cvt_pk_bf16_f32 v50, v51, v74
	v_cvt_pk_bf16_f32 v51, v75, v76
	v_cvt_pk_bf16_f32 v52, v77, v52
	v_cvt_pk_bf16_f32 v53, v53, v78
	v_mad_i64_i32 v[74:75], s[0:1], v115, s2, v[120:121]
	global_store_dwordx4 v[74:75], v[50:53], off sc1
	v_mov_b64_e32 v[76:77], v[64:65]
	v_mov_b64_e32 v[80:81], v[68:69]
	v_mov_b64_e32 v[50:51], v[70:71]
	v_mov_b64_e32 v[84:85], v[56:57]
	v_mov_b64_e32 v[88:89], v[60:61]
	v_mov_b64_e32 v[92:93], v[44:45]
	v_mov_b64_e32 v[96:97], v[48:49]
	v_mov_b64_e32 v[100:101], v[40:41]
	v_mov_b64_e32 v[104:105], v[36:37]
	v_mov_b64_e32 v[108:109], v[28:29]
	v_mov_b64_e32 v[112:113], v[32:33]
	v_add_u32_e32 v115, s23, v115
	v_mov_b64_e32 v[52:53], v[72:73]
	v_mov_b64_e32 v[74:75], v[62:63]
	v_mov_b64_e32 v[78:79], v[66:67]
	v_mov_b64_e32 v[82:83], v[54:55]
	v_mov_b64_e32 v[86:87], v[58:59]
	v_mov_b64_e32 v[90:91], v[42:43]
	v_mov_b64_e32 v[94:95], v[46:47]
	v_mov_b64_e32 v[98:99], v[38:39]
	v_mov_b64_e32 v[102:103], v[34:35]
	v_mov_b64_e32 v[106:107], v[26:27]
	v_mov_b64_e32 v[110:111], v[30:31]
	v_mov_b32_e32 v138, v146
	s_andn2_b64 exec, exec, s[18:19]
	s_cbranch_execz .LBB0_365

; #define POOL_ROW_LOAD(m_, A_, B_) do { const bool smp_ = (m_) >= MPROMPT; int b_, t_; if (smp_) { b_ = ((m_) - MPROMPT) / DS; t_ = ((m_) - MPROMPT) - b_ * DS; } else { b_ = (m_) / LP; t_ = (m_) - b_ * LP; } \
;         pool_load<4>(L_PROJ, L_state_pool, l, (m_), smp_, b_, t_, chA, winA, A_); pool_load<16>(L_PROJ, L_state_pool, l, (m_), smp_, b_, t_, chB, winB, B_); } while (0)
; template <int MAXW>
; __device__ __forceinline__ void pool_finish(bf16_t* DBUF, int m, bool sample, int t, int ch, int win, const u32x4 (&rw)[MAXW]) {
;     float acc[8], u0[8];
;     unpack8(rw[0], u0);
; #pragma unroll
;     for (int e = 0; e < 8; ++e) acc[e] = u0[e];
; #pragma unroll
;     for (int j = 1; j < MAXW; ++j) { float xv[8]; unpack8(rw[j], xv);
; #pragma unroll
;         for (int e = 0; e < 8; ++e) acc[e] += xv[e]; }
;     const int cnt = sample ? win : ((t + 1) < win ? (t + 1) : win);
;     const float inv = 1.0f / (float)cnt;
;     float d[8];
; #pragma unroll
;     for (int e = 0; e < 8; ++e) d[e] = acc[e] * inv - u0[e];
;     *(u32x4*)(DBUF + (size_t)m * 1024 + ch) = pack8(d);
; }
; __device__ __forceinline__ void mixer_elementwise(const Ctx& C_, int l) {
;     ...
;     for (; m < MREAL; m += NGW) {
;         const bool sample = m >= MPROMPT;
;         const int t = sample ? ((m - MPROMPT) % DS) : (m % LP);
;         const bool more = m + NGW < MREAL;
;         if (more) POOL_ROW_LOAD(m + NGW, nwA, nwB);
;         pool_finish<4>(L_DBUF, m, sample, t, chA, winA, rwA);
;         pool_finish<16>(L_DBUF, m, sample, t, chB, winB, rwB);
.LBB0_543:
	s_mul_hi_i32 s44, s52, 0xfe03f81
	s_lshr_b32 s45, s44, 31
	s_ashr_i32 s44, s44, 7
	s_add_i32 s44, s44, s45
	s_mulk_i32 s44, 0x810
	s_sub_i32 s58, s52, s44
	s_cmpk_gt_i32 s52, 0x407f
	s_cselect_b64 s[44:45], -1, 0
	s_and_b64 s[56:57], s[44:45], exec
	s_waitcnt vmcnt(0)
	v_lshlrev_b32_e32 v1, 16, v8
	v_lshlrev_b32_e32 v2, 16, v4
	s_cselect_b32 s52, s1, s58
	v_add_f32_e32 v1, v2, v1
	v_lshlrev_b32_e32 v199, 16, v12
	v_add_f32_e32 v1, v1, v199
	v_lshlrev_b32_e32 v199, 16, v16
	s_add_i32 s52, s52, 1
	v_add_f32_e32 v1, v1, v199
	v_min_i32_e32 v199, s52, v183
	v_cndmask_b32_e64 v199, v199, v183, s[44:45]
	v_cvt_f32_i32_e32 v199, v199
	v_and_b32_e32 v3, 0xffff0000, v4
	v_and_b32_e32 v186, 0xffff0000, v8
	v_add_f32_e32 v186, v3, v186
	v_lshlrev_b32_e32 v187, 16, v9
	v_lshlrev_b32_e32 v188, 16, v5
	v_and_b32_e32 v200, 0xffff0000, v12
	v_add_f32_e32 v187, v188, v187
	v_lshlrev_b32_e32 v201, 16, v13
	v_add_f32_e32 v186, v186, v200
	v_and_b32_e32 v200, 0xffff0000, v16
	v_add_f32_e32 v187, v187, v201
	v_lshlrev_b32_e32 v201, 16, v17
	v_add_f32_e32 v186, v186, v200
	v_div_scale_f32 v200, s[56:57], v199, v199, 1.0
	v_add_f32_e32 v187, v187, v201
	v_rcp_f32_e32 v201, v200
	v_and_b32_e32 v189, 0xffff0000, v5
	v_and_b32_e32 v190, 0xffff0000, v9
	v_add_f32_e32 v190, v189, v190
	v_and_b32_e32 v202, 0xffff0000, v13
	v_lshlrev_b32_e32 v191, 16, v10
	v_lshlrev_b32_e32 v192, 16, v6
	v_add_f32_e32 v190, v190, v202
	v_and_b32_e32 v202, 0xffff0000, v17
	v_add_f32_e32 v191, v192, v191
	v_and_b32_e32 v193, 0xffff0000, v6
	v_and_b32_e32 v194, 0xffff0000, v10
	v_lshlrev_b32_e32 v203, 16, v14
	v_add_f32_e32 v190, v190, v202
	v_fma_f32 v202, -v200, v201, 1.0
	v_add_f32_e32 v194, v193, v194
	v_and_b32_e32 v204, 0xffff0000, v14
	v_add_f32_e32 v191, v191, v203
	v_lshlrev_b32_e32 v203, 16, v18
	v_fmac_f32_e32 v201, v202, v201
	v_div_scale_f32 v202, vcc, 1.0, v199, 1.0
	v_add_f32_e32 v194, v194, v204
	v_and_b32_e32 v204, 0xffff0000, v18
	v_add_f32_e32 v191, v191, v203
	v_mul_f32_e32 v203, v202, v201
	v_add_f32_e32 v194, v194, v204
	v_fma_f32 v204, -v200, v203, v202
	v_and_b32_e32 v197, 0xffff0000, v7
	v_and_b32_e32 v198, 0xffff0000, v11
	v_fmac_f32_e32 v203, v204, v201
	v_lshlrev_b32_e32 v195, 16, v11
	v_lshlrev_b32_e32 v196, 16, v7
	v_add_f32_e32 v198, v197, v198
	v_and_b32_e32 v206, 0xffff0000, v15
	v_fma_f32 v200, -v200, v203, v202
	v_add_f32_e32 v195, v196, v195
	v_lshlrev_b32_e32 v205, 16, v15
	v_add_f32_e32 v198, v198, v206
	v_and_b32_e32 v206, 0xffff0000, v19
	v_div_fmas_f32 v200, v200, v201, v203
	v_add_f32_e32 v195, v195, v205
	v_lshlrev_b32_e32 v205, 16, v19
	v_add_f32_e32 v198, v198, v206
	v_div_fixup_f32 v199, v200, v199, 1.0
	v_add_f32_e32 v195, v195, v205
	v_fma_f32 v1, v1, v199, -v2
	v_fma_f32 v2, v186, v199, -v3
	v_fma_f32 v3, v187, v199, -v188
	v_fma_f32 v187, v190, v199, -v189
	v_fma_f32 v188, v191, v199, -v192
	v_fma_f32 v189, v194, v199, -v193
	v_fma_f32 v191, v198, v199, -v197
	v_fma_f32 v190, v195, v199, -v196
	v_cvt_pk_bf16_f32 v186, v1, v2
	v_cvt_pk_bf16_f32 v188, v188, v189
	v_cvt_pk_bf16_f32 v189, v190, v191
	v_lshlrev_b32_e32 v1, 16, v20
	v_lshlrev_b32_e32 v191, 16, v28
	v_add_f32_e32 v191, v191, v1
	v_lshlrev_b32_e32 v199, 16, v24
	v_add_f32_e32 v191, v191, v199
	v_lshlrev_b32_e32 v199, 16, v36
	v_add_f32_e32 v191, v191, v199
	v_lshlrev_b32_e32 v199, 16, v32
	v_add_f32_e32 v191, v191, v199
	v_lshlrev_b32_e32 v199, 16, v44
	v_add_f32_e32 v191, v191, v199
	v_lshlrev_b32_e32 v199, 16, v40
	v_and_b32_e32 v2, 0xffff0000, v20
	v_and_b32_e32 v192, 0xffff0000, v28
	v_add_f32_e32 v191, v191, v199
	v_lshlrev_b32_e32 v199, 16, v52
	v_cvt_pk_bf16_f32 v187, v3, v187
	v_lshlrev_b32_e32 v3, 16, v21
	v_lshlrev_b32_e32 v193, 16, v29
	v_add_f32_e32 v192, v192, v2
	v_and_b32_e32 v200, 0xffff0000, v24
	v_add_f32_e32 v191, v191, v199
	v_lshlrev_b32_e32 v199, 16, v48
	v_add_f32_e32 v193, v193, v3
	v_lshlrev_b32_e32 v201, 16, v25
	v_add_f32_e32 v192, v192, v200
	v_and_b32_e32 v200, 0xffff0000, v36
	v_add_f32_e32 v191, v191, v199
	v_lshlrev_b32_e32 v199, 16, v60
	v_add_f32_e32 v193, v193, v201
	v_lshlrev_b32_e32 v201, 16, v37
	v_add_f32_e32 v192, v192, v200
	v_and_b32_e32 v200, 0xffff0000, v32
	v_add_f32_e32 v191, v191, v199
	v_lshlrev_b32_e32 v199, 16, v56
	v_add_f32_e32 v193, v193, v201
	v_lshlrev_b32_e32 v201, 16, v33
	v_add_f32_e32 v192, v192, v200
	v_and_b32_e32 v200, 0xffff0000, v44
	v_add_f32_e32 v191, v191, v199
	v_lshlrev_b32_e32 v199, 16, v68
	global_store_dwordx4 v[180:181], v[186:189], off sc1
	v_and_b32_e32 v194, 0xffff0000, v29
	v_add_f32_e32 v193, v193, v201
	v_and_b32_e32 v186, 0xffff0000, v21
	v_lshlrev_b32_e32 v201, 16, v45
	v_add_f32_e32 v192, v192, v200
	v_and_b32_e32 v200, 0xffff0000, v40
	v_add_f32_e32 v191, v191, v199
	v_lshlrev_b32_e32 v199, 16, v64
	v_add_f32_e32 v194, v194, v186
	v_and_b32_e32 v202, 0xffff0000, v25
	v_add_f32_e32 v193, v193, v201
	v_lshlrev_b32_e32 v201, 16, v41
	v_add_f32_e32 v192, v192, v200
	v_and_b32_e32 v200, 0xffff0000, v52
	v_add_f32_e32 v191, v191, v199
	v_lshlrev_b32_e32 v199, 16, v76
	v_lshlrev_b32_e32 v187, 16, v22
	v_lshlrev_b32_e32 v195, 16, v30
	v_add_f32_e32 v194, v194, v202
	v_and_b32_e32 v202, 0xffff0000, v37
	v_add_f32_e32 v193, v193, v201
	v_lshlrev_b32_e32 v201, 16, v53
	v_add_f32_e32 v192, v192, v200
	v_and_b32_e32 v200, 0xffff0000, v48
	v_add_f32_e32 v191, v191, v199
	v_lshlrev_b32_e32 v199, 16, v72
	v_and_b32_e32 v188, 0xffff0000, v22
	v_and_b32_e32 v196, 0xffff0000, v30
	v_add_f32_e32 v195, v195, v187
	v_lshlrev_b32_e32 v203, 16, v26
	v_add_f32_e32 v194, v194, v202
	v_and_b32_e32 v202, 0xffff0000, v33
	v_add_f32_e32 v193, v193, v201
	v_lshlrev_b32_e32 v201, 16, v49
	v_add_f32_e32 v192, v192, v200
; template <int MAXW>
; __device__ __forceinline__ void pool_finish(bf16_t* DBUF, int m, bool sample, int t, int ch, int win, const u32x4 (&rw)[MAXW]) {
;     ...
;     for (int j = 1; j < MAXW; ++j) { float xv[8]; unpack8(rw[j], xv);
; #pragma unroll
;         for (int e = 0; e < 8; ++e) acc[e] += xv[e]; }
;     const int cnt = sample ? win : ((t + 1) < win ? (t + 1) : win);
;     const float inv = 1.0f / (float)cnt;
;     float d[8];
; #pragma unroll
;     for (int e = 0; e < 8; ++e) d[e] = acc[e] * inv - u0[e];
;     *(u32x4*)(DBUF + (size_t)m * 1024 + ch) = pack8(d);
; }
	v_and_b32_e32 v200, 0xffff0000, v60
	v_add_f32_e32 v191, v191, v199
	v_lshlrev_b32_e32 v199, 16, v80
	v_add_f32_e32 v196, v196, v188
	v_and_b32_e32 v204, 0xffff0000, v26
	v_add_f32_e32 v195, v195, v203
	v_lshlrev_b32_e32 v203, 16, v38
	v_add_f32_e32 v194, v194, v202
	v_and_b32_e32 v202, 0xffff0000, v45
	v_add_f32_e32 v193, v193, v201
	v_lshlrev_b32_e32 v201, 16, v61
	v_add_f32_e32 v192, v192, v200
	v_and_b32_e32 v200, 0xffff0000, v56
	v_add_f32_e32 v191, v191, v199
	v_min_i32_e32 v199, s52, v184
	v_add_f32_e32 v196, v196, v204
	v_and_b32_e32 v204, 0xffff0000, v38
	v_add_f32_e32 v195, v195, v203
	v_lshlrev_b32_e32 v203, 16, v34
	v_add_f32_e32 v194, v194, v202
	v_and_b32_e32 v202, 0xffff0000, v41
	v_add_f32_e32 v193, v193, v201
	v_lshlrev_b32_e32 v201, 16, v57
	v_add_f32_e32 v192, v192, v200
	v_and_b32_e32 v200, 0xffff0000, v68
	v_cndmask_b32_e64 v199, v199, v184, s[44:45]
	v_add_f32_e32 v196, v196, v204
	v_and_b32_e32 v204, 0xffff0000, v34
	v_add_f32_e32 v195, v195, v203
	v_lshlrev_b32_e32 v203, 16, v46
	v_add_f32_e32 v194, v194, v202
	v_and_b32_e32 v202, 0xffff0000, v53
	v_add_f32_e32 v193, v193, v201
	v_lshlrev_b32_e32 v201, 16, v69
	v_add_f32_e32 v192, v192, v200
	v_and_b32_e32 v200, 0xffff0000, v64
	v_cvt_f32_i32_e32 v199, v199
	v_lshlrev_b32_e32 v189, 16, v23
	v_lshlrev_b32_e32 v197, 16, v31
	v_add_f32_e32 v196, v196, v204
	v_and_b32_e32 v204, 0xffff0000, v46
	v_add_f32_e32 v195, v195, v203
	v_lshlrev_b32_e32 v203, 16, v42
	v_add_f32_e32 v194, v194, v202
	v_and_b32_e32 v202, 0xffff0000, v49
	v_add_f32_e32 v193, v193, v201
	v_lshlrev_b32_e32 v201, 16, v65
	v_add_f32_e32 v192, v192, v200
	v_and_b32_e32 v200, 0xffff0000, v76
	v_and_b32_e32 v190, 0xffff0000, v23
	v_and_b32_e32 v198, 0xffff0000, v31
	v_add_f32_e32 v197, v197, v189
	v_lshlrev_b32_e32 v205, 16, v27
	v_add_f32_e32 v196, v196, v204
	v_and_b32_e32 v204, 0xffff0000, v42
	v_add_f32_e32 v195, v195, v203
	v_lshlrev_b32_e32 v203, 16, v54
	v_add_f32_e32 v194, v194, v202
	v_and_b32_e32 v202, 0xffff0000, v61
	v_add_f32_e32 v193, v193, v201
	v_lshlrev_b32_e32 v201, 16, v77
	v_add_f32_e32 v192, v192, v200
	v_and_b32_e32 v200, 0xffff0000, v72
	v_add_f32_e32 v198, v198, v190
	v_and_b32_e32 v206, 0xffff0000, v27
	v_add_f32_e32 v197, v197, v205
	v_lshlrev_b32_e32 v205, 16, v39
	v_add_f32_e32 v196, v196, v204
	v_and_b32_e32 v204, 0xffff0000, v54
	v_add_f32_e32 v195, v195, v203
	v_lshlrev_b32_e32 v203, 16, v50
	v_add_f32_e32 v194, v194, v202
	v_and_b32_e32 v202, 0xffff0000, v57
	v_add_f32_e32 v193, v193, v201
	v_lshlrev_b32_e32 v201, 16, v73
	v_add_f32_e32 v192, v192, v200
	v_and_b32_e32 v200, 0xffff0000, v80
	v_add_f32_e32 v198, v198, v206
	v_and_b32_e32 v206, 0xffff0000, v39
	v_add_f32_e32 v197, v197, v205
	v_lshlrev_b32_e32 v205, 16, v35
	v_add_f32_e32 v196, v196, v204
	v_and_b32_e32 v204, 0xffff0000, v50
	v_add_f32_e32 v195, v195, v203
	v_lshlrev_b32_e32 v203, 16, v62
	v_add_f32_e32 v194, v194, v202
	v_and_b32_e32 v202, 0xffff0000, v69
	v_add_f32_e32 v193, v193, v201
	v_lshlrev_b32_e32 v201, 16, v81
	v_add_f32_e32 v192, v192, v200
	v_div_scale_f32 v200, s[44:45], v199, v199, 1.0
	v_add_f32_e32 v198, v198, v206
	v_and_b32_e32 v206, 0xffff0000, v35
	v_add_f32_e32 v197, v197, v205
	v_lshlrev_b32_e32 v205, 16, v47
	v_add_f32_e32 v196, v196, v204
	v_and_b32_e32 v204, 0xffff0000, v62
	v_add_f32_e32 v195, v195, v203
	v_lshlrev_b32_e32 v203, 16, v58
	v_add_f32_e32 v194, v194, v202
	v_and_b32_e32 v202, 0xffff0000, v65
	v_add_f32_e32 v193, v193, v201
	v_rcp_f32_e32 v201, v200
	v_add_f32_e32 v198, v198, v206
	v_and_b32_e32 v206, 0xffff0000, v47
	v_add_f32_e32 v197, v197, v205
	v_lshlrev_b32_e32 v205, 16, v43
	v_add_f32_e32 v196, v196, v204
	v_and_b32_e32 v204, 0xffff0000, v58
	v_add_f32_e32 v195, v195, v203
	v_lshlrev_b32_e32 v203, 16, v70
	v_add_f32_e32 v194, v194, v202
	v_and_b32_e32 v202, 0xffff0000, v77
	v_add_f32_e32 v198, v198, v206
	v_and_b32_e32 v206, 0xffff0000, v43
	v_add_f32_e32 v197, v197, v205
	v_lshlrev_b32_e32 v205, 16, v55
	v_add_f32_e32 v196, v196, v204
	v_and_b32_e32 v204, 0xffff0000, v70
	v_add_f32_e32 v195, v195, v203
	v_lshlrev_b32_e32 v203, 16, v66
	v_add_f32_e32 v194, v194, v202
	v_and_b32_e32 v202, 0xffff0000, v73
	v_add_f32_e32 v198, v198, v206
	v_and_b32_e32 v206, 0xffff0000, v55
	v_add_f32_e32 v197, v197, v205
	v_lshlrev_b32_e32 v205, 16, v51
	v_add_f32_e32 v196, v196, v204
	v_and_b32_e32 v204, 0xffff0000, v66
	v_add_f32_e32 v195, v195, v203
	v_lshlrev_b32_e32 v203, 16, v78
	v_add_f32_e32 v194, v194, v202
	v_and_b32_e32 v202, 0xffff0000, v81
	v_add_f32_e32 v198, v198, v206
	v_and_b32_e32 v206, 0xffff0000, v51
	v_add_f32_e32 v197, v197, v205
	v_lshlrev_b32_e32 v205, 16, v63
	v_add_f32_e32 v196, v196, v204
	v_and_b32_e32 v204, 0xffff0000, v78
	v_add_f32_e32 v195, v195, v203
	v_lshlrev_b32_e32 v203, 16, v74
	v_add_f32_e32 v194, v194, v202
	v_fma_f32 v202, -v200, v201, 1.0
	v_add_f32_e32 v198, v198, v206
	v_and_b32_e32 v206, 0xffff0000, v63
	v_add_f32_e32 v197, v197, v205
	v_lshlrev_b32_e32 v205, 16, v59
	v_add_f32_e32 v196, v196, v204
	v_and_b32_e32 v204, 0xffff0000, v74
	v_add_f32_e32 v195, v195, v203
	v_lshlrev_b32_e32 v203, 16, v82
	v_fmac_f32_e32 v201, v202, v201
	v_div_scale_f32 v202, vcc, 1.0, v199, 1.0
	v_add_f32_e32 v198, v198, v206
	v_and_b32_e32 v206, 0xffff0000, v59
	v_add_f32_e32 v197, v197, v205
	v_lshlrev_b32_e32 v205, 16, v71
	v_add_f32_e32 v196, v196, v204
	v_and_b32_e32 v204, 0xffff0000, v82
	v_add_f32_e32 v195, v195, v203
	v_mul_f32_e32 v203, v202, v201
	v_add_f32_e32 v198, v198, v206
	v_and_b32_e32 v206, 0xffff0000, v71
	v_add_f32_e32 v197, v197, v205
	v_lshlrev_b32_e32 v205, 16, v67
	v_add_f32_e32 v196, v196, v204
	v_fma_f32 v204, -v200, v203, v202
	v_add_f32_e32 v198, v198, v206
	v_and_b32_e32 v206, 0xffff0000, v67
	v_add_f32_e32 v197, v197, v205
	v_lshlrev_b32_e32 v205, 16, v79
	v_fmac_f32_e32 v203, v204, v201
	v_add_f32_e32 v198, v198, v206
	v_and_b32_e32 v206, 0xffff0000, v79
	v_add_f32_e32 v197, v197, v205
	v_lshlrev_b32_e32 v205, 16, v75
	v_fma_f32 v200, -v200, v203, v202
	v_add_f32_e32 v198, v198, v206
	v_and_b32_e32 v206, 0xffff0000, v75
	v_add_f32_e32 v197, v197, v205
	v_lshlrev_b32_e32 v205, 16, v83
	v_div_fmas_f32 v200, v200, v201, v203
	v_add_f32_e32 v198, v198, v206
	v_and_b32_e32 v206, 0xffff0000, v83
	v_add_f32_e32 v197, v197, v205
	v_div_fixup_f32 v199, v200, v199, 1.0
	v_add_f32_e32 v198, v198, v206
	v_fma_f32 v188, v196, v199, -v188
	v_fma_f32 v189, v197, v199, -v189
	s_andn2_b64 vcc, exec, s[80:81]
	v_fma_f32 v1, v191, v199, -v1
	v_fma_f32 v2, v192, v199, -v2
	v_fma_f32 v3, v193, v199, -v3
	v_fma_f32 v191, v194, v199, -v186
	v_fma_f32 v192, v195, v199, -v187
	v_fma_f32 v190, v198, v199, -v190
	v_cvt_pk_bf16_f32 v186, v1, v2
	v_cvt_pk_bf16_f32 v187, v3, v191
	v_cvt_pk_bf16_f32 v188, v192, v188
	v_cvt_pk_bf16_f32 v189, v189, v190
	global_store_dwordx4 v[180:181], v[186:189], off offset:1024 sc1
	s_cbranch_vccnz .LBB0_456
; __device__ __forceinline__ void mixer_elementwise(const Ctx& C_, int l) {
;     ...
;         if (more) {
; #pragma unroll
;             for (int j = 0; j < 4; ++j) rwA[j] = nwA[j];
; #pragma unroll
;             for (int j = 0; j < 16; ++j) rwB[j] = nwB[j];
;         }
	v_mov_b64_e32 v[12:13], v[92:93]
	v_mov_b64_e32 v[8:9], v[88:89]
	v_mov_b64_e32 v[4:5], v[84:85]
	v_mov_b64_e32 v[20:21], v[100:101]
	v_mov_b64_e32 v[14:15], v[94:95]
	v_mov_b64_e32 v[10:11], v[90:91]
	v_mov_b64_e32 v[6:7], v[86:87]
	v_mov_b64_e32 v[22:23], v[102:103]
	v_mov_b32_e32 v16, v96
	v_mov_b32_e32 v17, v97
	v_mov_b32_e32 v18, v98
	v_mov_b32_e32 v19, v99
	v_mov_b32_e32 v80, v160
	v_mov_b32_e32 v81, v161
	v_mov_b32_e32 v82, v162
	v_mov_b32_e32 v83, v163
	v_mov_b32_e32 v72, v152
	v_mov_b32_e32 v73, v153
	v_mov_b32_e32 v74, v154
	v_mov_b32_e32 v75, v155
	v_mov_b32_e32 v76, v156
	v_mov_b32_e32 v77, v157
	v_mov_b32_e32 v78, v158
	v_mov_b32_e32 v79, v159
	v_mov_b32_e32 v64, v144
	v_mov_b32_e32 v65, v145
	v_mov_b32_e32 v66, v146
	v_mov_b32_e32 v67, v147
	v_mov_b32_e32 v68, v148
	v_mov_b32_e32 v69, v149
	v_mov_b32_e32 v70, v150
	v_mov_b32_e32 v71, v151
	v_mov_b32_e32 v56, v136
	v_mov_b32_e32 v57, v137
	v_mov_b32_e32 v58, v138
	v_mov_b32_e32 v59, v139
	v_mov_b32_e32 v60, v140
	v_mov_b32_e32 v61, v141
	v_mov_b32_e32 v62, v142
	v_mov_b32_e32 v63, v143
	v_mov_b32_e32 v48, v128
	v_mov_b32_e32 v49, v129
	v_mov_b32_e32 v50, v130
	v_mov_b32_e32 v51, v131
	v_mov_b32_e32 v52, v132
	v_mov_b32_e32 v53, v133
	v_mov_b32_e32 v54, v134
	v_mov_b32_e32 v55, v135
	v_mov_b32_e32 v40, v120
	v_mov_b32_e32 v41, v121
	v_mov_b32_e32 v42, v122
	v_mov_b32_e32 v43, v123
	v_mov_b32_e32 v44, v124
	v_mov_b32_e32 v45, v125
	v_mov_b32_e32 v46, v126
	v_mov_b32_e32 v47, v127
	v_mov_b32_e32 v32, v112
	v_mov_b32_e32 v33, v113
	v_mov_b32_e32 v34, v114
	v_mov_b32_e32 v35, v115
	v_mov_b32_e32 v36, v116
	v_mov_b32_e32 v37, v117
	v_mov_b32_e32 v38, v118
	v_mov_b32_e32 v39, v119
	v_mov_b32_e32 v24, v104
	v_mov_b32_e32 v25, v105
	v_mov_b32_e32 v26, v106
	v_mov_b32_e32 v27, v107
	v_mov_b32_e32 v28, v108
	v_mov_b32_e32 v29, v109
	v_mov_b32_e32 v30, v110
	v_mov_b32_e32 v31, v111
	s_branch .LBB0_456

; __device__ __forceinline__ void ffn_half(const bf16_t* UP, const float* state_ffn, const f32x4 (&w)[3][2], const f32x4 (&bs)[2], int l, int m0, int t0, bool sample, int b, int col, float (&res)[8][8]) {
;     ...
;     for (int j = 0; j < 8; ++j) { res[j][0] = bs[0].x; res[j][1] = bs[0].y; res[j][2] = bs[0].z; res[j][3] = bs[0].w; res[j][4] = bs[1].x; res[j][5] = bs[1].y; res[j][6] = bs[1].z; res[j][7] = bs[1].w; }
; #pragma unroll
;     for (int i = 0; i < 10; ++i) {
;         float xv[8]; unpack8(raw[i], xv);
; #pragma unroll
;         for (int k = 0; k < 3; ++k) { const int j = i - k;
;             if (j >= 0 && j < 8) {
;                 res[j][0] += w[k][0].x * xv[0]; res[j][1] += w[k][0].y * xv[1]; res[j][2] += w[k][0].z * xv[2]; res[j][3] += w[k][0].w * xv[3];
;                 res[j][4] += w[k][1].x * xv[4]; res[j][5] += w[k][1].y * xv[5]; res[j][6] += w[k][1].z * xv[6]; res[j][7] += w[k][1].w * xv[7]; } }
;     }
.LBB0_1161:
	s_or_b64 exec, exec, s[22:23]
	s_waitcnt vmcnt(27)
	v_and_b32_e32 v1, 0xffff0000, v143
	v_lshlrev_b32_e32 v2, 16, v143
	v_and_b32_e32 v3, 0xffff0000, v142
	v_and_b32_e32 v143, 0xffff0000, v141
	v_lshlrev_b32_e32 v141, 16, v141
	v_and_b32_e32 v172, 0xffff0000, v140
	v_lshlrev_b32_e32 v140, 16, v140
	v_lshlrev_b32_e32 v142, 16, v142
	v_fma_f32 v140, v4, v140, v28
	v_fma_f32 v172, v5, v172, v29
	v_fma_f32 v141, v6, v141, v30
	v_fma_f32 v187, v9, v3, v33
	v_fma_f32 v188, v10, v2, v34
	v_fma_f32 v199, v11, v1, v35
	s_waitcnt vmcnt(26)
	v_lshlrev_b32_e32 v1, 16, v144
	v_and_b32_e32 v2, 0xffff0000, v144
	v_lshlrev_b32_e32 v3, 16, v145
	v_fma_f32 v173, v7, v143, v31
	v_fma_f32 v182, v8, v142, v32
	v_and_b32_e32 v142, 0xffff0000, v145
	v_lshlrev_b32_e32 v143, 16, v146
	v_and_b32_e32 v144, 0xffff0000, v146
	v_lshlrev_b32_e32 v145, 16, v147
	v_and_b32_e32 v146, 0xffff0000, v147
	v_fma_f32 v200, v4, v1, v28
	v_fma_f32 v203, v5, v2, v29
	v_fma_f32 v204, v6, v3, v30
	v_fmac_f32_e32 v140, v12, v1
	v_fmac_f32_e32 v172, v13, v2
	v_fmac_f32_e32 v141, v14, v3
	s_waitcnt vmcnt(25)
	v_lshlrev_b32_e32 v1, 16, v136
	v_and_b32_e32 v2, 0xffff0000, v136
	v_lshlrev_b32_e32 v3, 16, v137
	v_fma_f32 v205, v7, v142, v31
	v_fma_f32 v206, v8, v143, v32
	v_fma_f32 v208, v10, v145, v34
	v_fma_f32 v209, v11, v146, v35
	v_fmac_f32_e32 v173, v15, v142
	v_fmac_f32_e32 v182, v16, v143
	v_fmac_f32_e32 v199, v19, v146
	v_lshlrev_b32_e32 v142, 16, v138
	v_lshlrev_b32_e32 v143, 16, v139
	v_fma_f32 v146, v4, v1, v28
	v_fma_f32 v210, v5, v2, v29
	v_fma_f32 v211, v6, v3, v30
	v_fmac_f32_e32 v200, v12, v1
	v_fmac_f32_e32 v203, v13, v2
	v_fmac_f32_e32 v204, v14, v3
	v_fmac_f32_e32 v140, v20, v1
	v_fmac_f32_e32 v172, v21, v2
	v_fmac_f32_e32 v141, v22, v3
	s_waitcnt vmcnt(24)
	v_lshlrev_b32_e32 v1, 16, v132
	v_and_b32_e32 v2, 0xffff0000, v132
	v_lshlrev_b32_e32 v3, 16, v133
	v_fma_f32 v207, v9, v144, v33
	v_fmac_f32_e32 v187, v17, v144
	v_fmac_f32_e32 v188, v18, v145
	v_and_b32_e32 v138, 0xffff0000, v138
	v_fma_f32 v213, v8, v142, v32
	v_fma_f32 v215, v10, v143, v34
	v_fmac_f32_e32 v206, v16, v142
	v_fmac_f32_e32 v208, v18, v143
	v_fmac_f32_e32 v182, v24, v142
	v_lshlrev_b32_e32 v142, 16, v135
	v_fma_f32 v216, v4, v1, v28
	v_fma_f32 v217, v5, v2, v29
	v_fma_f32 v218, v6, v3, v30
	v_fmac_f32_e32 v146, v12, v1
	v_fmac_f32_e32 v210, v13, v2
	v_fmac_f32_e32 v211, v14, v3
	v_fmac_f32_e32 v200, v20, v1
	v_fmac_f32_e32 v203, v21, v2
	v_fmac_f32_e32 v204, v22, v3
	s_waitcnt vmcnt(23)
	v_lshlrev_b32_e32 v1, 16, v128
	v_and_b32_e32 v2, 0xffff0000, v128
	v_lshlrev_b32_e32 v3, 16, v129
	v_and_b32_e32 v128, 0xffff0000, v129
	v_lshlrev_b32_e32 v129, 16, v130
	v_fma_f32 v214, v9, v138, v33
	v_fmac_f32_e32 v207, v17, v138
	v_fmac_f32_e32 v187, v25, v138
	v_fmac_f32_e32 v188, v26, v143
	v_fma_f32 v138, v10, v142, v34
	v_fmac_f32_e32 v215, v18, v142
	v_fmac_f32_e32 v208, v26, v142
	v_and_b32_e32 v130, 0xffff0000, v130
	v_fma_f32 v221, v4, v1, v28
	v_fma_f32 v222, v5, v2, v29
	v_fma_f32 v223, v6, v3, v30
	v_fma_f32 v142, v7, v128, v31
	v_fma_f32 v143, v8, v129, v32
	v_fmac_f32_e32 v216, v12, v1
	v_fmac_f32_e32 v217, v13, v2
	v_fmac_f32_e32 v218, v14, v3
	v_fmac_f32_e32 v146, v20, v1
	v_fmac_f32_e32 v210, v21, v2
	v_fmac_f32_e32 v211, v22, v3
	s_waitcnt vmcnt(22)
	v_lshlrev_b32_e32 v1, 16, v124
	v_and_b32_e32 v2, 0xffff0000, v124
	v_lshlrev_b32_e32 v3, 16, v125
	v_and_b32_e32 v124, 0xffff0000, v125
	v_lshlrev_b32_e32 v125, 16, v126
	v_fma_f32 v144, v9, v130, v33
	v_and_b32_e32 v126, 0xffff0000, v126
	v_fma_f32 v224, v4, v1, v28
	v_fma_f32 v225, v5, v2, v29
	v_fma_f32 v226, v6, v3, v30
	v_fma_f32 v227, v7, v124, v31
	v_fma_f32 v183, v8, v125, v32
	v_fmac_f32_e32 v221, v12, v1
	v_fmac_f32_e32 v222, v13, v2
	v_fmac_f32_e32 v223, v14, v3
	v_fmac_f32_e32 v142, v15, v124
	v_fmac_f32_e32 v143, v16, v125
	v_fmac_f32_e32 v216, v20, v1
	v_fmac_f32_e32 v217, v21, v2
	v_fmac_f32_e32 v218, v22, v3
	s_waitcnt vmcnt(21)
	v_lshlrev_b32_e32 v1, 16, v120
	v_and_b32_e32 v2, 0xffff0000, v120
	v_lshlrev_b32_e32 v3, 16, v121
	v_and_b32_e32 v120, 0xffff0000, v121
	v_lshlrev_b32_e32 v121, 16, v122
	v_fma_f32 v184, v9, v126, v33
	v_fmac_f32_e32 v144, v17, v126
	v_and_b32_e32 v122, 0xffff0000, v122
	v_fma_f32 v228, v4, v1, v28
	v_fma_f32 v229, v5, v2, v29
	v_fma_f32 v190, v7, v120, v31
	v_fma_f32 v191, v8, v121, v32
	v_fmac_f32_e32 v224, v12, v1
	v_fmac_f32_e32 v225, v13, v2
	v_fmac_f32_e32 v227, v15, v120
	v_fmac_f32_e32 v183, v16, v121
	v_fmac_f32_e32 v221, v20, v1
	v_fmac_f32_e32 v142, v23, v120
	v_fmac_f32_e32 v143, v24, v121
	s_waitcnt vmcnt(20)
	v_lshlrev_b32_e32 v1, 16, v116
	v_and_b32_e32 v116, 0xffff0000, v116
	v_lshlrev_b32_e32 v120, 16, v117
	v_and_b32_e32 v117, 0xffff0000, v117
	v_lshlrev_b32_e32 v121, 16, v118
	v_fma_f32 v192, v9, v122, v33
	v_fmac_f32_e32 v184, v17, v122
	v_fmac_f32_e32 v222, v21, v2
	v_fmac_f32_e32 v144, v25, v122
	v_and_b32_e32 v118, 0xffff0000, v118
	v_lshlrev_b32_e32 v122, 16, v119
	v_fma_f32 v196, v5, v116, v29
	v_fma_f32 v198, v7, v117, v31
	v_fma_f32 v2, v8, v121, v32
	v_fmac_f32_e32 v229, v13, v116
	v_fmac_f32_e32 v190, v15, v117
	v_fmac_f32_e32 v225, v21, v116
	v_fmac_f32_e32 v227, v23, v117
	s_waitcnt vmcnt(19)
	v_lshlrev_b32_e32 v116, 16, v113
	v_and_b32_e32 v113, 0xffff0000, v113
	v_lshlrev_b32_e32 v117, 16, v114
	v_and_b32_e32 v139, 0xffff0000, v139
	v_fma_f32 v189, v6, v3, v30
	v_fmac_f32_e32 v226, v14, v3
	v_fmac_f32_e32 v223, v22, v3
	v_fma_f32 v3, v9, v118, v33
	v_fma_f32 v201, v10, v122, v34
	v_fmac_f32_e32 v192, v17, v118
	v_fmac_f32_e32 v184, v25, v118
	v_and_b32_e32 v114, 0xffff0000, v114
	v_lshlrev_b32_e32 v118, 16, v115
	v_fmac_f32_e32 v198, v15, v113
	v_fmac_f32_e32 v2, v16, v117
	v_fmac_f32_e32 v190, v23, v113
	s_waitcnt vmcnt(18)
; __device__ __forceinline__ float siluf_(float x) { return x * sigmoidf_(x); }
; __device__ __forceinline__ void ffn_half(const bf16_t* UP, const float* state_ffn, const f32x4 (&w)[3][2], const f32x4 (&bs)[2], int l, int m0, int t0, bool sample, int b, int col, float (&res)[8][8]) {
;     ...
;     for (int i = 0; i < 10; ++i) {
;         float xv[8]; unpack8(raw[i], xv);
; #pragma unroll
;         for (int k = 0; k < 3; ++k) { const int j = i - k;
;             if (j >= 0 && j < 8) {
;                 res[j][0] += w[k][0].x * xv[0]; res[j][1] += w[k][0].y * xv[1]; res[j][2] += w[k][0].z * xv[2]; res[j][3] += w[k][0].w * xv[3];
;                 res[j][4] += w[k][1].x * xv[4]; res[j][5] += w[k][1].y * xv[5]; res[j][6] += w[k][1].z * xv[6]; res[j][7] += w[k][1].w * xv[7]; } }
;     }
; __device__ __forceinline__ void ffn_elementwise(const Ctx& C_, int l) {
;     ...
;         for (int j = 0; j < 8; ++j)
; #pragma unroll
;             for (int e = 0; e < 8; ++e) gate[j][e] = siluf_(gate[j][e]);
	v_lshlrev_b32_e32 v113, 16, v110
	v_fmac_f32_e32 v199, v27, v139
	v_fmac_f32_e32 v3, v17, v114
	v_fmac_f32_e32 v201, v18, v118
	v_fmac_f32_e32 v192, v25, v114
	v_lshlrev_b32_e32 v114, 16, v111
	v_fmac_f32_e32 v2, v24, v113
	v_mul_f32_e32 v113, 0xbfb8aa3b, v188
	v_fmac_f32_e32 v201, v26, v114
	v_exp_f32_e32 v113, v113
	v_mul_f32_e32 v114, 0xbfb8aa3b, v199
	v_exp_f32_e32 v114, v114
	v_and_b32_e32 v137, 0xffff0000, v137
	v_fma_f32 v195, v4, v1, v28
	v_fma_f32 v197, v6, v120, v30
	v_fmac_f32_e32 v228, v12, v1
	v_fmac_f32_e32 v224, v20, v1
	v_lshlrev_b32_e32 v1, 16, v112
	v_and_b32_e32 v112, 0xffff0000, v112
	v_fma_f32 v212, v7, v137, v31
	v_and_b32_e32 v132, 0xffff0000, v133
	v_fmac_f32_e32 v196, v13, v112
	v_fmac_f32_e32 v197, v14, v116
	v_fmac_f32_e32 v229, v21, v112
	v_lshlrev_b32_e32 v112, 16, v109
	v_add_f32_e32 v113, 1.0, v113
	v_fma_f32 v219, v7, v132, v31
	v_fmac_f32_e32 v212, v15, v132
	v_fmac_f32_e32 v197, v22, v112
	v_mul_f32_e32 v112, 0xbfb8aa3b, v187
	v_rcp_f32_e32 v113, v113
	v_add_f32_e32 v114, 1.0, v114
	v_fmac_f32_e32 v219, v15, v128
	v_fmac_f32_e32 v212, v23, v128
	v_lshlrev_b32_e32 v128, 16, v127
	v_exp_f32_e32 v112, v112
	v_rcp_f32_e32 v114, v114
	v_fma_f32 v185, v10, v128, v34
	v_fmac_f32_e32 v219, v23, v124
	v_lshlrev_b32_e32 v124, 16, v123
	v_and_b32_e32 v123, 0xffff0000, v123
	v_fma_f32 v194, v11, v123, v35
	v_fmac_f32_e32 v185, v18, v124
	v_and_b32_e32 v119, 0xffff0000, v119
	v_fma_f32 v202, v11, v119, v35
	v_fmac_f32_e32 v194, v19, v119
	v_fmac_f32_e32 v185, v26, v122
	v_and_b32_e32 v115, 0xffff0000, v115
	v_mul_f32_e32 v113, v188, v113
	v_mul_f32_e32 v188, 0xbfb8aa3b, v184
	v_fmac_f32_e32 v202, v19, v115
	v_fmac_f32_e32 v194, v27, v115
	v_add_f32_e32 v112, 1.0, v112
	v_mul_f32_e32 v115, 0xbfb8aa3b, v200
	v_mul_f32_e32 v114, v199, v114
	v_exp_f32_e32 v188, v188
	v_mul_f32_e32 v199, 0xbfb8aa3b, v185
	v_rcp_f32_e32 v112, v112
	v_exp_f32_e32 v115, v115
	v_exp_f32_e32 v199, v199
	v_fmac_f32_e32 v183, v24, v121
	v_add_f32_e32 v188, 1.0, v188
	v_mul_f32_e32 v112, v187, v112
	v_add_f32_e32 v115, 1.0, v115
	v_mul_f32_e32 v187, 0xbfb8aa3b, v183
	v_rcp_f32_e32 v188, v188
	v_add_f32_e32 v199, 1.0, v199
	v_and_b32_e32 v127, 0xffff0000, v127
	v_fmac_f32_e32 v189, v14, v120
	v_rcp_f32_e32 v115, v115
	v_exp_f32_e32 v187, v187
	v_rcp_f32_e32 v199, v199
	v_fma_f32 v186, v11, v127, v35
	v_fmac_f32_e32 v189, v22, v116
	v_mul_f32_e32 v116, 0xbfb8aa3b, v203
	v_fmac_f32_e32 v186, v19, v123
	v_fmac_f32_e32 v228, v20, v1
	v_exp_f32_e32 v116, v116
	v_fmac_f32_e32 v186, v27, v119
	v_mul_f32_e32 v184, v184, v188
	v_mul_f32_e32 v188, 0xbfb8aa3b, v228
	v_mul_f32_e32 v115, v200, v115
	v_add_f32_e32 v187, 1.0, v187
	v_mul_f32_e32 v200, 0xbfb8aa3b, v186
	v_mul_f32_e32 v185, v185, v199
	v_exp_f32_e32 v188, v188
	v_mul_f32_e32 v199, 0xbfb8aa3b, v229
	v_rcp_f32_e32 v187, v187
	v_exp_f32_e32 v200, v200
	v_exp_f32_e32 v199, v199
	v_add_f32_e32 v116, 1.0, v116
	v_rcp_f32_e32 v116, v116
	v_add_f32_e32 v188, 1.0, v188
	v_mul_f32_e32 v183, v183, v187
	v_add_f32_e32 v187, 1.0, v200
	v_rcp_f32_e32 v200, v188
	v_add_f32_e32 v188, 1.0, v199
	v_rcp_f32_e32 v199, v188
	v_mul_f32_e32 v188, 0xbfb8aa3b, v189
	v_mul_f32_e32 v116, v203, v116
	v_rcp_f32_e32 v187, v187
	v_exp_f32_e32 v203, v188
	v_fmac_f32_e32 v191, v16, v121
	v_fmac_f32_e32 v191, v24, v117
	v_mul_f32_e32 v188, v186, v187
	v_mul_f32_e32 v186, v228, v200
	v_mul_f32_e32 v187, v229, v199
	v_add_f32_e32 v199, 1.0, v203
	v_mul_f32_e32 v200, 0xbfb8aa3b, v190
	v_mul_f32_e32 v203, 0xbfb8aa3b, v191
	v_exp_f32_e32 v200, v200
	v_exp_f32_e32 v203, v203
	v_fma_f32 v136, v11, v139, v35
	v_fmac_f32_e32 v205, v15, v137
	v_and_b32_e32 v135, 0xffff0000, v135
	v_lshlrev_b32_e32 v133, 16, v134
	v_and_b32_e32 v134, 0xffff0000, v134
	v_fmac_f32_e32 v136, v19, v135
	v_fmac_f32_e32 v205, v23, v132
	v_lshlrev_b32_e32 v132, 16, v131
	v_and_b32_e32 v131, 0xffff0000, v131
	v_mul_f32_e32 v117, 0xbfb8aa3b, v204
	v_add_f32_e32 v200, 1.0, v200
	v_add_f32_e32 v203, 1.0, v203
	v_fmac_f32_e32 v173, v23, v137
	v_fma_f32 v137, v9, v134, v33
	v_fmac_f32_e32 v214, v17, v134
	v_fmac_f32_e32 v136, v27, v131
	v_fmac_f32_e32 v195, v12, v1
	v_lshlrev_b32_e32 v1, 16, v108
	v_and_b32_e32 v109, 0xffff0000, v109
	v_exp_f32_e32 v117, v117
	v_rcp_f32_e32 v200, v200
	v_rcp_f32_e32 v203, v203
	v_fmac_f32_e32 v137, v17, v130
	v_fmac_f32_e32 v214, v25, v130
	v_fma_f32 v193, v10, v124, v34
	v_fmac_f32_e32 v195, v20, v1
	v_fmac_f32_e32 v198, v23, v109
	v_mul_f32_e32 v1, 0xbfb8aa3b, v140
	v_mul_f32_e32 v109, 0xbfb8aa3b, v141
	v_mul_f32_e32 v130, 0xbfb8aa3b, v136
	v_fmac_f32_e32 v193, v18, v122
	v_exp_f32_e32 v1, v1
	v_exp_f32_e32 v109, v109
	v_exp_f32_e32 v130, v130
	v_fmac_f32_e32 v209, v19, v139
	v_fmac_f32_e32 v193, v26, v118
	v_fmac_f32_e32 v209, v27, v135
	v_fma_f32 v145, v10, v132, v34
	v_fma_f32 v147, v11, v131, v35
	v_fmac_f32_e32 v138, v18, v132
	v_fmac_f32_e32 v215, v26, v132
	v_add_f32_e32 v117, 1.0, v117
	v_mul_f32_e32 v132, 0xbfb8aa3b, v217
	v_mul_f32_e32 v190, v190, v200
	v_mul_f32_e32 v191, v191, v203
	v_mul_f32_e32 v200, 0xbfb8aa3b, v193
	v_mul_f32_e32 v203, 0xbfb8aa3b, v194
	v_fmac_f32_e32 v147, v19, v127
	v_and_b32_e32 v108, 0xffff0000, v108
	v_rcp_f32_e32 v117, v117
	v_mul_f32_e32 v122, 0xbfb8aa3b, v209
	v_exp_f32_e32 v132, v132
	v_exp_f32_e32 v200, v200
	v_exp_f32_e32 v203, v203
	v_fmac_f32_e32 v147, v27, v123
	v_fmac_f32_e32 v196, v21, v108
	v_mul_f32_e32 v108, 0xbfb8aa3b, v172
	v_add_f32_e32 v1, 1.0, v1
	v_add_f32_e32 v109, 1.0, v109
	v_mul_f32_e32 v121, 0xbfb8aa3b, v208
	v_exp_f32_e32 v122, v122
	v_mul_f32_e32 v123, 0xbfb8aa3b, v146
	v_add_f32_e32 v130, 1.0, v130
	v_exp_f32_e32 v108, v108
	v_rcp_f32_e32 v1, v1
	v_rcp_f32_e32 v109, v109
; __device__ __forceinline__ float sigmoidf_(float x) { return __builtin_amdgcn_rcpf(1.0f + __expf(-x)); }
; __device__ __forceinline__ float siluf_(float x) { return x * sigmoidf_(x); }
; __device__ __forceinline__ void ffn_elementwise(const Ctx& C_, int l) {
;     ...
;         for (int j = 0; j < 8; ++j)
; #pragma unroll
;             for (int e = 0; e < 8; ++e) gate[j][e] = siluf_(gate[j][e]);
	v_exp_f32_e32 v121, v121
	v_exp_f32_e32 v123, v123
	v_rcp_f32_e32 v130, v130
	v_fma_f32 v139, v11, v135, v35
	v_fmac_f32_e32 v139, v19, v131
	v_mul_f32_e32 v117, v204, v117
	v_add_f32_e32 v132, 1.0, v132
	v_mul_f32_e32 v204, 0xbfb8aa3b, v192
	v_add_f32_e32 v200, 1.0, v200
	v_add_f32_e32 v203, 1.0, v203
	v_fma_f32 v220, v8, v133, v32
	v_fmac_f32_e32 v213, v16, v133
	v_fmac_f32_e32 v206, v24, v133
	v_fmac_f32_e32 v145, v18, v128
	v_fmac_f32_e32 v137, v25, v126
	v_fmac_f32_e32 v138, v26, v128
	v_fmac_f32_e32 v139, v27, v127
	v_and_b32_e32 v110, 0xffff0000, v110
	v_add_f32_e32 v122, 1.0, v122
	v_rcp_f32_e32 v133, v132
	v_mul_f32_e32 v132, 0xbfb8aa3b, v218
	v_rcp_f32_e32 v199, v199
	v_exp_f32_e32 v204, v204
	v_rcp_f32_e32 v200, v200
	v_rcp_f32_e32 v203, v203
	v_fmac_f32_e32 v207, v25, v134
	v_fmac_f32_e32 v220, v16, v129
	v_fmac_f32_e32 v145, v26, v124
	v_fmac_f32_e32 v3, v25, v110
	v_add_f32_e32 v108, 1.0, v108
	v_mul_f32_e32 v1, v140, v1
	v_mul_f32_e32 v110, 0xbfb8aa3b, v173
	v_mul_f32_e32 v109, v141, v109
	v_add_f32_e32 v121, 1.0, v121
	v_rcp_f32_e32 v124, v122
	v_add_f32_e32 v122, 1.0, v123
	v_exp_f32_e32 v134, v132
	v_mul_f32_e32 v132, v136, v130
	v_mul_f32_e32 v136, 0xbfb8aa3b, v137
	v_mul_f32_e32 v140, 0xbfb8aa3b, v138
	v_mul_f32_e32 v141, 0xbfb8aa3b, v139
	v_fmac_f32_e32 v220, v24, v125
	v_rcp_f32_e32 v108, v108
	v_exp_f32_e32 v110, v110
	v_rcp_f32_e32 v121, v121
	v_rcp_f32_e32 v125, v122
	v_exp_f32_e32 v136, v136
	v_exp_f32_e32 v140, v140
	v_exp_f32_e32 v141, v141
	v_mul_f32_e32 v189, v189, v199
	v_add_f32_e32 v199, 1.0, v204
	v_mul_f32_e32 v204, 0xbfb8aa3b, v195
	v_mul_f32_e32 v193, v193, v200
	v_mul_f32_e32 v194, v194, v203
	v_mul_f32_e32 v200, 0xbfb8aa3b, v196
	v_mul_f32_e32 v203, 0xbfb8aa3b, v197
	v_and_b32_e32 v111, 0xffff0000, v111
	v_mul_f32_e32 v122, 0xbfb8aa3b, v210
	v_rcp_f32_e32 v199, v199
	v_exp_f32_e32 v204, v204
	v_exp_f32_e32 v200, v200
	v_exp_f32_e32 v203, v203
	v_fmac_f32_e32 v202, v27, v111
	v_mul_f32_e32 v108, v172, v108
	v_mul_f32_e32 v111, 0xbfb8aa3b, v182
	v_add_f32_e32 v110, 1.0, v110
	v_exp_f32_e32 v126, v122
	v_mul_f32_e32 v122, v208, v121
	v_mul_f32_e32 v121, v146, v125
	v_add_f32_e32 v136, 1.0, v136
	v_add_f32_e32 v140, 1.0, v140
	v_add_f32_e32 v141, 1.0, v141
	v_mul_f32_e32 v146, 0xbfb8aa3b, v221
	v_mul_f32_e32 v172, 0xbfb8aa3b, v143
	v_exp_f32_e32 v111, v111
	v_rcp_f32_e32 v110, v110
	v_rcp_f32_e32 v136, v136
	v_rcp_f32_e32 v140, v140
	v_rcp_f32_e32 v141, v141
	v_exp_f32_e32 v146, v146
	v_exp_f32_e32 v172, v172
	v_mul_f32_e32 v192, v192, v199
	v_add_f32_e32 v199, 1.0, v204
	v_add_f32_e32 v200, 1.0, v200
	v_add_f32_e32 v203, 1.0, v203
	v_mul_f32_e32 v204, 0xbfb8aa3b, v198
	v_rcp_f32_e32 v199, v199
	v_rcp_f32_e32 v200, v200
	v_rcp_f32_e32 v203, v203
	v_exp_f32_e32 v204, v204
	v_add_f32_e32 v111, 1.0, v111
	v_mul_f32_e32 v110, v173, v110
	v_mul_f32_e32 v136, v137, v136
	v_mul_f32_e32 v137, v138, v140
	v_mul_f32_e32 v138, v139, v141
	v_add_f32_e32 v139, 1.0, v146
	v_mul_f32_e32 v146, 0xbfb8aa3b, v142
	v_mul_f32_e32 v173, 0xbfb8aa3b, v144
	v_add_f32_e32 v172, 1.0, v172
	v_rcp_f32_e32 v111, v111
	v_exp_f32_e32 v146, v146
	v_exp_f32_e32 v173, v173
	v_rcp_f32_e32 v172, v172
	v_mul_f32_e32 v195, v195, v199
	v_mul_f32_e32 v196, v196, v200
	v_mul_f32_e32 v197, v197, v203
	v_add_f32_e32 v199, 1.0, v204
	v_mul_f32_e32 v200, 0xbfb8aa3b, v2
	v_mul_f32_e32 v203, 0xbfb8aa3b, v3
	v_rcp_f32_e32 v199, v199
	v_exp_f32_e32 v200, v200
	v_exp_f32_e32 v203, v203
	v_mul_f32_e32 v111, v182, v111
	v_add_f32_e32 v146, 1.0, v146
	v_add_f32_e32 v173, 1.0, v173
	v_mul_f32_e32 v182, 0xbfb8aa3b, v145
	v_mul_f32_e32 v143, v143, v172
	v_mul_f32_e32 v172, 0xbfb8aa3b, v147
	v_rcp_f32_e32 v146, v146
	v_rcp_f32_e32 v173, v173
	v_exp_f32_e32 v182, v182
	v_exp_f32_e32 v172, v172
	v_mul_f32_e32 v198, v198, v199
	v_add_f32_e32 v199, 1.0, v200
	v_add_f32_e32 v200, 1.0, v203
	v_mul_f32_e32 v203, 0xbfb8aa3b, v201
	v_mul_f32_e32 v204, 0xbfb8aa3b, v202
	v_mul_f32_e32 v118, 0xbfb8aa3b, v205
	v_mul_f32_e32 v123, v209, v124
	v_add_f32_e32 v124, 1.0, v126
	v_mul_f32_e32 v126, 0xbfb8aa3b, v212
	v_mul_f32_e32 v131, 0xbfb8aa3b, v216
	v_mul_f32_e32 v135, 0xbfb8aa3b, v220
	v_exp_f32_e32 v203, v203
	v_exp_f32_e32 v204, v204
	v_exp_f32_e32 v118, v118
	v_exp_f32_e32 v126, v126
	v_exp_f32_e32 v131, v131
	v_exp_f32_e32 v135, v135
	v_mul_f32_e32 v142, v142, v146
	v_mul_f32_e32 v144, v144, v173
	v_add_f32_e32 v146, 1.0, v182
	v_mul_f32_e32 v173, 0xbfb8aa3b, v224
	v_add_f32_e32 v172, 1.0, v172
	v_mul_f32_e32 v182, 0xbfb8aa3b, v225
	v_fmac_f32_e32 v226, v22, v120
	v_mul_f32_e32 v119, 0xbfb8aa3b, v206
	v_mul_f32_e32 v120, 0xbfb8aa3b, v207
	v_exp_f32_e32 v173, v173
	v_rcp_f32_e32 v172, v172
	v_exp_f32_e32 v182, v182
	v_exp_f32_e32 v119, v119
	v_exp_f32_e32 v120, v120
	v_mul_f32_e32 v125, 0xbfb8aa3b, v211
	v_add_f32_e32 v203, 1.0, v203
	v_add_f32_e32 v204, 1.0, v204
	v_add_f32_e32 v118, 1.0, v118
	v_exp_f32_e32 v125, v125
	v_add_f32_e32 v126, 1.0, v126
	v_add_f32_e32 v131, 1.0, v131
	v_add_f32_e32 v135, 1.0, v135
	v_rcp_f32_e32 v199, v199
	v_rcp_f32_e32 v200, v200
	v_rcp_f32_e32 v203, v203
	v_rcp_f32_e32 v204, v204
	v_rcp_f32_e32 v118, v118
	v_rcp_f32_e32 v126, v126
	v_rcp_f32_e32 v131, v131
	v_rcp_f32_e32 v135, v135
	v_add_f32_e32 v173, 1.0, v173
	v_mul_f32_e32 v147, v147, v172
	v_add_f32_e32 v172, 1.0, v182
	v_fmac_f32_e32 v213, v24, v129
	v_add_f32_e32 v119, 1.0, v119
	v_add_f32_e32 v120, 1.0, v120
	v_rcp_f32_e32 v146, v146
	v_rcp_f32_e32 v173, v173
	v_rcp_f32_e32 v172, v172
	v_rcp_f32_e32 v119, v119
	v_rcp_f32_e32 v120, v120
	v_mul_f32_e32 v127, 0xbfb8aa3b, v213
	v_mul_f32_e32 v128, 0xbfb8aa3b, v214
	v_mul_f32_e32 v129, 0xbfb8aa3b, v215
	v_add_f32_e32 v125, 1.0, v125
	v_exp_f32_e32 v127, v127
	v_exp_f32_e32 v128, v128
	v_exp_f32_e32 v129, v129
	v_mul_f32_e32 v199, v2, v199
	v_mul_f32_e32 v200, v3, v200
	v_mul_f32_e32 v201, v201, v203
	v_mul_f32_e32 v202, v202, v204
	s_waitcnt vmcnt(9)
; __device__ __forceinline__ void ffn_half(const bf16_t* UP, const float* state_ffn, const f32x4 (&w)[3][2], const f32x4 (&bs)[2], int l, int m0, int t0, bool sample, int b, int col, float (&res)[8][8]) {
;     ...
;     for (int i = 0; i < 10; ++i) {
;         float xv[8]; unpack8(raw[i], xv);
; #pragma unroll
;         for (int k = 0; k < 3; ++k) { const int j = i - k;
;             if (j >= 0 && j < 8) {
;                 res[j][0] += w[k][0].x * xv[0]; res[j][1] += w[k][0].y * xv[1]; res[j][2] += w[k][0].z * xv[2]; res[j][3] += w[k][0].w * xv[3];
;                 res[j][4] += w[k][1].x * xv[4]; res[j][5] += w[k][1].y * xv[5]; res[j][6] += w[k][1].z * xv[6]; res[j][7] += w[k][1].w * xv[7]; } }
;     }
; __device__ __forceinline__ void ffn_elementwise(const Ctx& C_, int l) {
;     ...
;         for (int k = 0; k < 3; ++k) { wv[k][0] = *(const f32x4*)(fw + (size_t)k * DUP + DFF + v * 8); wv[k][1] = *(const f32x4*)(fw + (size_t)k * DUP + DFF + v * 8 + 4); }
;         bv[0] = *(const f32x4*)(fb + DFF + v * 8); bv[1] = *(const f32x4*)(fb + DFF + v * 8 + 4);
;         ffn_half(L_UP, L_state_ffn, wv, bv, l, m0, t0, sample, b, DFF + v * 8, val);
	v_and_b32_e32 v2, 0xffff0000, v107
	v_lshlrev_b32_e32 v3, 16, v107
	v_and_b32_e32 v107, 0xffff0000, v106
	v_lshlrev_b32_e32 v106, 16, v106
	v_and_b32_e32 v203, 0xffff0000, v105
	v_lshlrev_b32_e32 v105, 16, v105
	v_and_b32_e32 v204, 0xffff0000, v104
	v_lshlrev_b32_e32 v104, 16, v104
	v_mul_f32_e32 v118, v205, v118
	v_rcp_f32_e32 v124, v124
	v_rcp_f32_e32 v125, v125
	v_mul_f32_e32 v126, v212, v126
	v_mul_f32_e32 v130, v216, v131
	v_mul_f32_e32 v131, v217, v133
	v_add_f32_e32 v133, 1.0, v134
	v_mul_f32_e32 v134, 0xbfb8aa3b, v219
	v_mul_f32_e32 v135, v220, v135
	v_fma_f32 v205, v68, v104, v48
	v_fma_f32 v212, v70, v105, v50
	v_fma_f32 v216, v52, v106, v40
	v_fma_f32 v220, v53, v107, v41
	s_waitcnt vmcnt(8)
	v_lshlrev_b32_e32 v105, 16, v100
	s_waitcnt vmcnt(7)
	v_lshlrev_b32_e32 v104, 16, v96
	v_mov_b32_e32 v106, v44
	v_mov_b32_e32 v107, v92
	v_exp_f32_e32 v134, v134
	v_mul_f32_e32 v146, v145, v146
	v_mul_f32_e32 v145, v224, v173
	v_mul_f32_e32 v172, v225, v172
	v_fma_f32 v224, v54, v3, v42
	v_fma_f32 v225, v55, v2, v43
	v_pk_mul_f32 v[2:3], v[106:107], v[104:105]
	v_mul_f32_e32 v119, v206, v119
	v_mul_f32_e32 v120, v207, v120
	v_mul_f32_e32 v140, 0xbfb8aa3b, v222
	v_mul_f32_e32 v141, 0xbfb8aa3b, v223
	v_fma_f32 v208, v69, v204, v49
	v_add_f32_e32 v3, v3, v205
	v_and_b32_e32 v205, 0xffff0000, v100
	v_and_b32_e32 v204, 0xffff0000, v96
	v_mov_b32_e32 v206, v45
	v_mov_b32_e32 v207, v93
	v_add_f32_e32 v127, 1.0, v127
	v_add_f32_e32 v128, 1.0, v128
	v_add_f32_e32 v129, 1.0, v129
	v_exp_f32_e32 v140, v140
	v_exp_f32_e32 v141, v141
	v_add_f32_e32 v237, v2, v3
	v_pk_mul_f32 v[2:3], v[206:207], v[204:205]
	v_mul_f32_e32 v124, v210, v124
	v_mul_f32_e32 v125, v211, v125
	v_rcp_f32_e32 v127, v127
	v_rcp_f32_e32 v128, v128
	v_rcp_f32_e32 v129, v129
	v_add_f32_e32 v3, v3, v208
	v_lshlrev_b32_e32 v208, 16, v97
	v_lshlrev_b32_e32 v209, 16, v101
	v_mov_b32_e32 v210, v46
	v_mov_b32_e32 v211, v94
	v_add_f32_e32 v134, 1.0, v134
	v_add_f32_e32 v239, v2, v3
	v_pk_mul_f32 v[2:3], v[210:211], v[208:209]
	v_rcp_f32_e32 v133, v133
	v_rcp_f32_e32 v134, v134
	v_add_f32_e32 v3, v3, v212
	v_and_b32_e32 v101, 0xffff0000, v101
	v_and_b32_e32 v100, 0xffff0000, v97
	v_mov_b32_e32 v96, v47
	v_mov_b32_e32 v97, v95
	v_add_f32_e32 v140, 1.0, v140
	v_add_f32_e32 v141, 1.0, v141
	v_fma_f32 v203, v71, v203, v51
	v_add_f32_e32 v245, v2, v3
	v_pk_mul_f32 v[2:3], v[96:97], v[100:101]
	v_mul_f32_e32 v127, v213, v127
	v_mul_f32_e32 v128, v214, v128
	v_mul_f32_e32 v129, v215, v129
	v_rcp_f32_e32 v139, v139
	v_rcp_f32_e32 v140, v140
	v_rcp_f32_e32 v141, v141
	v_mul_f32_e32 v173, 0xbfb8aa3b, v226
	v_mul_f32_e32 v182, 0xbfb8aa3b, v227
	v_add_f32_e32 v3, v3, v203
	v_lshlrev_b32_e32 v213, 16, v102
	v_lshlrev_b32_e32 v212, 16, v98
	v_mov_b32_e32 v214, v36
	v_mov_b32_e32 v215, v80
	v_exp_f32_e32 v173, v173
	v_exp_f32_e32 v182, v182
	v_add_f32_e32 v203, v2, v3
	v_pk_mul_f32 v[2:3], v[214:215], v[212:213]
	v_mul_f32_e32 v133, v218, v133
	v_mul_f32_e32 v134, v219, v134
	v_add_f32_e32 v3, v3, v216
	v_and_b32_e32 v217, 0xffff0000, v102
	v_and_b32_e32 v216, 0xffff0000, v98
	v_mov_b32_e32 v218, v37
	v_mov_b32_e32 v219, v81
	v_add_f32_e32 v248, v2, v3
	v_pk_mul_f32 v[2:3], v[218:219], v[216:217]
	v_mul_f32_e32 v139, v221, v139
	v_mul_f32_e32 v140, v222, v140
	v_mul_f32_e32 v141, v223, v141
	v_add_f32_e32 v3, v3, v220
	v_lshlrev_b32_e32 v220, 16, v99
	v_lshlrev_b32_e32 v221, 16, v103
	v_mov_b32_e32 v222, v38
	v_mov_b32_e32 v223, v82
	v_add_f32_e32 v173, 1.0, v173
	v_add_f32_e32 v182, 1.0, v182
	v_add_f32_e32 v250, v2, v3
	v_pk_mul_f32 v[2:3], v[222:223], v[220:221]
	v_rcp_f32_e32 v173, v173
	v_rcp_f32_e32 v182, v182
	v_add_f32_e32 v3, v3, v224
	v_and_b32_e32 v103, 0xffff0000, v103
	v_and_b32_e32 v102, 0xffff0000, v99
	v_mov_b32_e32 v98, v39
	v_mov_b32_e32 v99, v83
	v_add_f32_e32 v252, v2, v3
	v_pk_mul_f32 v[2:3], v[98:99], v[102:103]
	s_waitcnt vmcnt(6)
	v_lshlrev_b32_e32 v224, 16, v84
	v_add_f32_e32 v3, v3, v225
	v_add_f32_e32 v230, v2, v3
	s_waitcnt vmcnt(5)
	v_lshlrev_b32_e32 v225, 16, v88
	v_mov_b32_e32 v2, v92
	v_mov_b32_e32 v3, v44
	v_mul_f32_e32 v173, v226, v173
	v_mul_f32_e32 v182, v227, v182
	v_fma_f32 v236, v68, v105, v48
	v_fma_f32 v105, v68, v104, v48
	v_pk_mul_f32 v[226:227], v[2:3], v[224:225]
	v_mov_b32_e32 v228, v224
	v_mov_b32_e32 v229, v104
	v_add_f32_e32 v44, v105, v226
	v_pk_mul_f32 v[104:105], v[106:107], v[228:229]
	v_add_f32_e32 v227, v44, v227
	v_add_f32_e32 v92, v105, v236
	v_add_f32_e32 v226, v104, v92
	v_and_b32_e32 v104, 0xffff0000, v84
	v_and_b32_e32 v105, 0xffff0000, v88
	v_mov_b32_e32 v44, v93
	v_mov_b32_e32 v106, v104
	v_mov_b32_e32 v107, v204
	v_fma_f32 v238, v69, v205, v49
	v_fma_f32 v205, v69, v204, v49
	v_pk_mul_f32 v[92:93], v[44:45], v[104:105]
	v_pk_mul_f32 v[106:107], v[206:207], v[106:107]
	v_add_f32_e32 v84, v205, v92
	v_add_f32_e32 v88, v107, v238
	v_add_f32_e32 v236, v106, v88
	v_add_f32_e32 v254, v84, v93
	v_lshlrev_b32_e32 v107, 16, v89
	v_lshlrev_b32_e32 v106, 16, v85
	v_mov_b32_e32 v92, v94
	v_mov_b32_e32 v93, v46
	v_fma_f32 v244, v70, v209, v50
	v_fma_f32 v209, v70, v208, v50
	v_pk_mul_f32 v[204:205], v[92:93], v[106:107]
	v_mov_b32_e32 v206, v106
	v_add_f32_e32 v46, v209, v204
	v_mov_b32_e32 v207, v208
	v_and_b32_e32 v88, 0xffff0000, v85
	v_pk_mul_f32 v[206:207], v[210:211], v[206:207]
	v_add_f32_e32 v210, v46, v205
	v_mov_b32_e32 v46, v95
	v_mov_b32_e32 v94, v88
	v_mov_b32_e32 v95, v100
	v_fma_f32 v246, v71, v101, v51
	v_add_f32_e32 v84, v207, v244
	v_and_b32_e32 v89, 0xffff0000, v89
	v_pk_mul_f32 v[94:95], v[96:97], v[94:95]
	v_fma_f32 v101, v71, v100, v51
	v_add_f32_e32 v208, v206, v84
	v_pk_mul_f32 v[84:85], v[46:47], v[88:89]
	v_add_f32_e32 v95, v95, v246
; __device__ __forceinline__ void ffn_half(const bf16_t* UP, const float* state_ffn, const f32x4 (&w)[3][2], const f32x4 (&bs)[2], int l, int m0, int t0, bool sample, int b, int col, float (&res)[8][8]) {
;     ...
;     for (int i = 0; i < 10; ++i) {
;         float xv[8]; unpack8(raw[i], xv);
; #pragma unroll
;         for (int k = 0; k < 3; ++k) { const int j = i - k;
;             if (j >= 0 && j < 8) {
;                 res[j][0] += w[k][0].x * xv[0]; res[j][1] += w[k][0].y * xv[1]; res[j][2] += w[k][0].z * xv[2]; res[j][3] += w[k][0].w * xv[3];
;                 res[j][4] += w[k][1].x * xv[4]; res[j][5] += w[k][1].y * xv[5]; res[j][6] += w[k][1].z * xv[6]; res[j][7] += w[k][1].w * xv[7]; } }
;     }
	v_add_f32_e32 v84, v101, v84
	v_add_f32_e32 v244, v94, v95
	v_lshlrev_b32_e32 v94, 16, v86
	v_add_f32_e32 v241, v84, v85
	v_lshlrev_b32_e32 v95, 16, v90
	v_mov_b32_e32 v84, v80
	v_mov_b32_e32 v85, v36
	v_mov_b32_e32 v100, v94
	v_mov_b32_e32 v101, v212
	v_fma_f32 v247, v52, v213, v40
	v_fma_f32 v213, v52, v212, v40
	v_pk_mul_f32 v[96:97], v[84:85], v[94:95]
	v_pk_mul_f32 v[100:101], v[214:215], v[100:101]
	v_add_f32_e32 v36, v213, v96
	v_add_f32_e32 v80, v101, v247
	v_and_b32_e32 v96, 0xffff0000, v86
	v_add_f32_e32 v212, v100, v80
	v_add_f32_e32 v214, v36, v97
	v_and_b32_e32 v97, 0xffff0000, v90
	v_mov_b32_e32 v36, v81
	v_mov_b32_e32 v100, v96
	v_mov_b32_e32 v101, v216
	v_fma_f32 v249, v53, v217, v41
	v_fma_f32 v217, v53, v216, v41
	v_pk_mul_f32 v[80:81], v[36:37], v[96:97]
	v_pk_mul_f32 v[100:101], v[218:219], v[100:101]
	v_add_f32_e32 v80, v217, v80
	v_add_f32_e32 v86, v101, v249
	v_add_f32_e32 v216, v100, v86
	v_add_f32_e32 v218, v80, v81
	v_lshlrev_b32_e32 v101, 16, v91
	v_lshlrev_b32_e32 v100, 16, v87
	v_mov_b32_e32 v80, v82
	v_mov_b32_e32 v81, v38
	v_fma_f32 v251, v54, v221, v42
	v_fma_f32 v221, v54, v220, v42
	v_pk_mul_f32 v[204:205], v[80:81], v[100:101]
	v_mov_b32_e32 v206, v100
	v_mov_b32_e32 v207, v220
	v_add_f32_e32 v38, v221, v204
	v_pk_mul_f32 v[206:207], v[222:223], v[206:207]
	v_add_f32_e32 v205, v38, v205
	v_add_f32_e32 v82, v207, v251
	v_and_b32_e32 v91, 0xffff0000, v91
	v_and_b32_e32 v90, 0xffff0000, v87
	v_mov_b32_e32 v38, v83
	v_fma_f32 v253, v55, v103, v43
	v_fma_f32 v103, v55, v102, v43
	v_add_f32_e32 v204, v206, v82
	v_pk_mul_f32 v[82:83], v[38:39], v[90:91]
	v_mov_b32_e32 v86, v90
	v_mov_b32_e32 v87, v102
	v_add_f32_e32 v82, v103, v82
	v_pk_mul_f32 v[86:87], v[98:99], v[86:87]
	v_add_f32_e32 v222, v82, v83
	v_add_f32_e32 v87, v87, v253
	s_waitcnt vmcnt(3)
	v_lshlrev_b32_e32 v83, 16, v76
	v_lshlrev_b32_e32 v82, 16, v72
	v_fma_f32 v228, v68, v225, v48
	v_add_f32_e32 v220, v86, v87
	v_pk_mul_f32 v[86:87], v[2:3], v[82:83]
	v_pk_mov_b32 v[98:99], v[224:225], v[82:83] op_sel:[1,0]
	v_fma_f32 v235, v68, v224, v48
	v_add_f32_e32 v86, v228, v86
	v_pk_mul_f32 v[98:99], v[2:3], v[98:99]
	v_add_f32_e32 v228, v86, v87
	v_add_f32_e32 v98, v235, v98
	v_and_b32_e32 v87, 0xffff0000, v76
	v_and_b32_e32 v86, 0xffff0000, v72
	v_fma_f32 v238, v69, v105, v49
	v_add_f32_e32 v224, v98, v99
	v_pk_mul_f32 v[98:99], v[44:45], v[86:87]
	v_pk_mov_b32 v[102:103], v[104:105], v[86:87] op_sel:[1,0]
	v_add_f32_e32 v72, v238, v98
	v_add_f32_e32 v247, v72, v99
	v_lshlrev_b32_e32 v99, 16, v77
	v_lshlrev_b32_e32 v98, 16, v73
	v_fma_f32 v229, v69, v104, v49
	v_pk_mul_f32 v[102:103], v[44:45], v[102:103]
	v_pk_mov_b32 v[104:105], v[106:107], v[98:99] op_sel:[1,0]
	v_fma_f32 v240, v70, v106, v50
	v_add_f32_e32 v76, v229, v102
	v_pk_mul_f32 v[104:105], v[92:93], v[104:105]
	v_fma_f32 v209, v70, v107, v50
	v_add_f32_e32 v229, v76, v103
	v_pk_mul_f32 v[102:103], v[92:93], v[98:99]
	v_add_f32_e32 v76, v240, v104
	v_add_f32_e32 v72, v209, v102
	v_add_f32_e32 v102, v76, v105
	v_and_b32_e32 v77, 0xffff0000, v77
	v_and_b32_e32 v76, 0xffff0000, v73
	v_fma_f32 v211, v71, v88, v51
	v_fma_f32 v246, v71, v89, v51
	v_add_f32_e32 v103, v72, v103
	v_pk_mul_f32 v[72:73], v[46:47], v[76:77]
	v_pk_mov_b32 v[88:89], v[88:89], v[76:77] op_sel:[1,0]
	v_add_f32_e32 v72, v246, v72
	v_pk_mul_f32 v[88:89], v[46:47], v[88:89]
	v_add_f32_e32 v209, v72, v73
	v_add_f32_e32 v88, v211, v88
	v_lshlrev_b32_e32 v73, 16, v78
	v_lshlrev_b32_e32 v72, 16, v74
	v_fma_f32 v242, v52, v94, v40
	v_fma_f32 v213, v52, v95, v40
	v_add_f32_e32 v106, v88, v89
	v_pk_mul_f32 v[88:89], v[84:85], v[72:73]
	v_pk_mov_b32 v[94:95], v[94:95], v[72:73] op_sel:[1,0]
	v_add_f32_e32 v88, v213, v88
	v_pk_mul_f32 v[94:95], v[84:85], v[94:95]
	v_fma_f32 v217, v53, v97, v41
	v_add_f32_e32 v94, v242, v94
	v_add_f32_e32 v242, v88, v89
	v_and_b32_e32 v89, 0xffff0000, v78
	v_and_b32_e32 v88, 0xffff0000, v74
	v_add_f32_e32 v213, v94, v95
	v_pk_mul_f32 v[94:95], v[36:37], v[88:89]
	v_fma_f32 v215, v53, v96, v41
	v_add_f32_e32 v74, v217, v94
	v_pk_mov_b32 v[96:97], v[96:97], v[88:89] op_sel:[1,0]
	v_add_f32_e32 v251, v74, v95
	v_lshlrev_b32_e32 v95, 16, v79
	v_lshlrev_b32_e32 v94, 16, v75
	v_fma_f32 v219, v54, v100, v42
	v_fma_f32 v206, v54, v101, v42
	v_pk_mul_f32 v[96:97], v[36:37], v[96:97]
	v_pk_mov_b32 v[100:101], v[100:101], v[94:95] op_sel:[1,0]
	v_add_f32_e32 v78, v215, v96
	v_pk_mul_f32 v[100:101], v[80:81], v[100:101]
	v_add_f32_e32 v215, v78, v97
	v_pk_mul_f32 v[96:97], v[80:81], v[94:95]
	v_add_f32_e32 v78, v219, v100
	v_add_f32_e32 v74, v206, v96
	v_add_f32_e32 v96, v78, v101
	v_and_b32_e32 v79, 0xffff0000, v79
	v_and_b32_e32 v78, 0xffff0000, v75
	v_fma_f32 v221, v55, v91, v43
	v_add_f32_e32 v97, v74, v97
	v_pk_mul_f32 v[74:75], v[38:39], v[78:79]
	v_fma_f32 v207, v55, v90, v43
	v_add_f32_e32 v74, v221, v74
	v_pk_mov_b32 v[90:91], v[90:91], v[78:79] op_sel:[1,0]
	v_add_f32_e32 v219, v74, v75
	s_waitcnt vmcnt(2)
	v_lshlrev_b32_e32 v74, 16, v60
	s_waitcnt vmcnt(1)
; __device__ __forceinline__ void ffn_half(const bf16_t* UP, const float* state_ffn, const f32x4 (&w)[3][2], const f32x4 (&bs)[2], int l, int m0, int t0, bool sample, int b, int col, float (&res)[8][8]) {
;     ...
;     for (int i = 0; i < 10; ++i) {
;         float xv[8]; unpack8(raw[i], xv);
; #pragma unroll
;         for (int k = 0; k < 3; ++k) { const int j = i - k;
;             if (j >= 0 && j < 8) {
;                 res[j][0] += w[k][0].x * xv[0]; res[j][1] += w[k][0].y * xv[1]; res[j][2] += w[k][0].z * xv[2]; res[j][3] += w[k][0].w * xv[3];
;                 res[j][4] += w[k][1].x * xv[4]; res[j][5] += w[k][1].y * xv[5]; res[j][6] += w[k][1].z * xv[6]; res[j][7] += w[k][1].w * xv[7]; } }
;     }
	v_lshlrev_b32_e32 v75, 16, v64
	v_fma_f32 v223, v68, v82, v48
	v_fma_f32 v225, v68, v83, v48
	v_pk_mul_f32 v[90:91], v[38:39], v[90:91]
	v_pk_mov_b32 v[82:83], v[82:83], v[74:75] op_sel:[1,0]
	v_add_f32_e32 v90, v207, v90
	v_pk_mul_f32 v[82:83], v[2:3], v[82:83]
	v_add_f32_e32 v206, v90, v91
	v_fma_f32 v221, v68, v74, v48
	v_pk_mul_f32 v[90:91], v[2:3], v[74:75]
	v_add_f32_e32 v68, v223, v82
	v_add_f32_e32 v48, v225, v90
	v_add_f32_e32 v74, v68, v83
	v_and_b32_e32 v83, 0xffff0000, v64
	v_and_b32_e32 v82, 0xffff0000, v60
	v_fma_f32 v235, v69, v86, v49
	v_fma_f32 v238, v69, v87, v49
	v_add_f32_e32 v90, v48, v91
	v_fma_f32 v91, v69, v82, v49
	v_pk_mul_f32 v[48:49], v[44:45], v[82:83]
	v_pk_mov_b32 v[68:69], v[86:87], v[82:83] op_sel:[1,0]
	v_add_f32_e32 v48, v238, v48
	v_pk_mul_f32 v[68:69], v[44:45], v[68:69]
	v_add_f32_e32 v223, v48, v49
	v_add_f32_e32 v60, v235, v68
	v_lshlrev_b32_e32 v48, 16, v61
	v_lshlrev_b32_e32 v49, 16, v65
	v_fma_f32 v104, v70, v99, v50
	v_add_f32_e32 v82, v60, v69
	v_pk_mul_f32 v[68:69], v[92:93], v[48:49]
	v_pk_mov_b32 v[86:87], v[98:99], v[48:49] op_sel:[1,0]
	v_fma_f32 v249, v70, v98, v50
	v_add_f32_e32 v60, v104, v68
	v_pk_mul_f32 v[86:87], v[92:93], v[86:87]
	v_and_b32_e32 v65, 0xffff0000, v65
	v_and_b32_e32 v64, 0xffff0000, v61
	v_fma_f32 v107, v71, v77, v51
	v_fma_f32 v50, v70, v48, v50
	v_add_f32_e32 v48, v249, v86
	v_add_f32_e32 v86, v60, v69
	v_pk_mul_f32 v[60:61], v[46:47], v[64:65]
	v_pk_mov_b32 v[68:69], v[76:77], v[64:65] op_sel:[1,0]
	v_fma_f32 v105, v71, v76, v51
	v_add_f32_e32 v60, v107, v60
	v_pk_mul_f32 v[68:69], v[46:47], v[68:69]
	v_add_f32_e32 v48, v48, v87
	v_fmac_f32_e32 v51, v71, v64
	v_add_f32_e32 v64, v105, v68
	v_add_f32_e32 v87, v60, v61
	v_lshlrev_b32_e32 v60, 16, v62
	v_lshlrev_b32_e32 v61, 16, v66
	v_fma_f32 v240, v52, v73, v40
	v_add_f32_e32 v64, v64, v69
	v_pk_mul_f32 v[68:69], v[84:85], v[60:61]
	v_pk_mov_b32 v[70:71], v[72:73], v[60:61] op_sel:[1,0]
	v_fma_f32 v211, v52, v72, v40
	v_fma_f32 v76, v52, v60, v40
	v_add_f32_e32 v40, v240, v68
	v_pk_mul_f32 v[70:71], v[84:85], v[70:71]
	v_add_f32_e32 v98, v40, v69
	v_add_f32_e32 v52, v211, v70
	v_and_b32_e32 v69, 0xffff0000, v66
	v_and_b32_e32 v68, 0xffff0000, v62
	v_fma_f32 v246, v53, v88, v41
	v_fma_f32 v217, v53, v89, v41
	v_add_f32_e32 v60, v52, v71
	v_fma_f32 v99, v53, v68, v41
	v_pk_mul_f32 v[40:41], v[36:37], v[68:69]
	v_pk_mov_b32 v[52:53], v[88:89], v[68:69] op_sel:[1,0]
	v_add_f32_e32 v40, v217, v40
	v_pk_mul_f32 v[52:53], v[36:37], v[52:53]
	v_add_f32_e32 v88, v40, v41
	v_add_f32_e32 v52, v246, v52
	v_lshlrev_b32_e32 v40, 16, v63
	v_lshlrev_b32_e32 v41, 16, v67
	v_fma_f32 v100, v54, v95, v42
	v_add_f32_e32 v68, v52, v53
	v_pk_mul_f32 v[52:53], v[80:81], v[40:41]
	v_pk_mov_b32 v[70:71], v[94:95], v[40:41] op_sel:[1,0]
	v_add_f32_e32 v52, v100, v52
	v_fma_f32 v253, v54, v94, v42
	v_pk_mul_f32 v[70:71], v[80:81], v[70:71]
	v_add_f32_e32 v94, v52, v53
	v_and_b32_e32 v53, 0xffff0000, v67
	v_and_b32_e32 v52, 0xffff0000, v63
	v_fma_f32 v101, v55, v78, v43
	v_fma_f32 v207, v55, v79, v43
	v_fma_f32 v42, v54, v40, v42
	v_add_f32_e32 v40, v253, v70
	v_fmac_f32_e32 v43, v55, v52
	v_pk_mul_f32 v[54:55], v[38:39], v[52:53]
	v_add_f32_e32 v89, v40, v71
	v_add_f32_e32 v40, v207, v54
	v_pk_mov_b32 v[62:63], v[78:79], v[52:53] op_sel:[1,0]
	v_add_f32_e32 v78, v40, v55
	v_pk_mul_f32 v[62:63], v[38:39], v[62:63]
	s_waitcnt vmcnt(0)
; __device__ __forceinline__ void ffn_elementwise(const Ctx& C_, int l) {
;     ...
; #pragma unroll
;         for (int j = 0; j < 8; ++j) { float a[8];
; #pragma unroll
;             for (int e = 0; e < 8; ++e) a[e] = gate[j][e] * val[j][e];
;             *(u32x4*)(L_ACT + (size_t)(m0 + j) * DFF + v * 8) = pack8(a); }
	v_lshlrev_b32_e32 v55, 16, v56
	v_mov_b32_e32 v54, v75
	v_add_f32_e32 v52, v101, v62
	v_pk_mul_f32 v[2:3], v[2:3], v[54:55]
	v_add_f32_e32 v52, v52, v63
	v_and_b32_e32 v63, 0xffff0000, v56
	v_add_f32_e32 v2, v221, v2
	v_mov_b32_e32 v62, v83
	v_add_f32_e32 v54, v2, v3
	v_pk_mul_f32 v[2:3], v[44:45], v[62:63]
	v_lshlrev_b32_e32 v67, 16, v57
	v_add_f32_e32 v2, v91, v2
	v_mov_b32_e32 v66, v49
	v_add_f32_e32 v44, v2, v3
	v_pk_mul_f32 v[2:3], v[92:93], v[66:67]
	v_and_b32_e32 v57, 0xffff0000, v57
	v_add_f32_e32 v2, v50, v2
	v_mov_b32_e32 v56, v65
	v_add_f32_e32 v45, v2, v3
	v_pk_mul_f32 v[2:3], v[46:47], v[56:57]
	v_lshlrev_b32_e32 v71, 16, v58
	v_add_f32_e32 v2, v51, v2
	v_mov_b32_e32 v70, v61
	v_add_f32_e32 v46, v2, v3
	v_pk_mul_f32 v[2:3], v[84:85], v[70:71]
	v_and_b32_e32 v73, 0xffff0000, v58
	v_add_f32_e32 v2, v76, v2
	v_mov_b32_e32 v72, v69
	v_add_f32_e32 v47, v2, v3
	v_pk_mul_f32 v[2:3], v[36:37], v[72:73]
	v_lshlrev_b32_e32 v77, 16, v59
	v_add_f32_e32 v2, v99, v2
	v_mov_b32_e32 v76, v41
	v_add_f32_e32 v49, v2, v3
	v_pk_mul_f32 v[2:3], v[80:81], v[76:77]
	v_and_b32_e32 v59, 0xffff0000, v59
	v_add_f32_e32 v2, v42, v2
	v_mov_b32_e32 v58, v53
	v_add_f32_e32 v42, v2, v3
	v_pk_mul_f32 v[2:3], v[38:39], v[58:59]
	v_mul_f32_e32 v37, v110, v203
	v_add_f32_e32 v2, v43, v2
	v_add_f32_e32 v43, v2, v3
	v_mul_f32_e32 v2, v108, v239
	v_mul_f32_e32 v3, v109, v245
	v_mul_f32_e32 v1, v1, v237
	v_mul_f32_e32 v38, v111, v248
	v_mul_f32_e32 v39, v112, v250
	v_mul_f32_e32 v40, v113, v252
	v_cvt_pk_bf16_f32 v36, v1, v2
	v_cvt_pk_bf16_f32 v37, v3, v37
	v_lshl_add_u64 v[2:3], s[10:11], 0, v[166:167]
	s_mov_b32 s2, 0x399c4000
	v_mul_f32_e32 v41, v114, v230
	v_cvt_pk_bf16_f32 v38, v38, v39
	v_cvt_pk_bf16_f32 v39, v40, v41
	v_add_co_u32_e32 v40, vcc, s2, v2
	s_mov_b32 s2, 0x399c5000
	s_nop 0
	v_addc_co_u32_e32 v41, vcc, 0, v3, vcc
	global_store_dwordx4 v[40:41], v[36:39], off sc1
	v_mul_f32_e32 v40, v120, v216
	v_mul_f32_e32 v41, v122, v204
	v_mul_f32_e32 v37, v117, v208
	v_mul_f32_e32 v38, v118, v244
	v_mul_f32_e32 v39, v119, v212
	v_cvt_pk_bf16_f32 v37, v37, v38
	v_cvt_pk_bf16_f32 v38, v39, v40
	v_add_co_u32_e32 v40, vcc, s2, v2
	v_mul_f32_e32 v36, v116, v236
	v_mul_f32_e32 v50, v123, v220
	v_cvt_pk_bf16_f32 v39, v41, v50
	v_addc_co_u32_e32 v41, vcc, 0, v3, vcc
	v_mul_f32_e32 v1, v115, v226
	v_cvt_pk_bf16_f32 v36, v1, v36
	global_store_dwordx4 v[40:41], v[36:39], off offset:1536 sc1
	v_mul_f32_e32 v40, v128, v218
	s_mov_b32 s2, 0x399c6000
	v_mul_f32_e32 v37, v125, v210
	v_mul_f32_e32 v38, v126, v241
	v_mul_f32_e32 v39, v127, v214
	v_mul_f32_e32 v41, v129, v205
	v_cvt_pk_bf16_f32 v37, v37, v38
	v_cvt_pk_bf16_f32 v38, v39, v40
	v_add_co_u32_e32 v40, vcc, s2, v2
	v_mul_f32_e32 v36, v124, v254
	v_mul_f32_e32 v50, v132, v222
	v_cvt_pk_bf16_f32 v39, v41, v50
	v_addc_co_u32_e32 v41, vcc, 0, v3, vcc
	v_mul_f32_e32 v1, v121, v227
	v_cvt_pk_bf16_f32 v36, v1, v36
	global_store_dwordx4 v[40:41], v[36:39], off offset:3072 sc1
	v_mul_f32_e32 v40, v136, v215
	s_mov_b32 s2, 0x399c8000
	v_mul_f32_e32 v37, v133, v102
	v_mul_f32_e32 v38, v134, v106
	v_mul_f32_e32 v39, v135, v213
	v_mul_f32_e32 v41, v137, v96
	v_cvt_pk_bf16_f32 v37, v37, v38
	v_cvt_pk_bf16_f32 v38, v39, v40
	v_add_co_u32_e32 v40, vcc, s2, v2
	v_mul_f32_e32 v36, v131, v229
	v_mul_f32_e32 v50, v138, v206
	v_cvt_pk_bf16_f32 v39, v41, v50
	v_addc_co_u32_e32 v41, vcc, 0, v3, vcc
	v_mul_f32_e32 v1, v130, v224
	v_cvt_pk_bf16_f32 v36, v1, v36
	global_store_dwordx4 v[40:41], v[36:39], off offset:512 sc1
	v_mul_f32_e32 v40, v144, v251
	s_mov_b32 s2, 0x399c9000
	v_mul_f32_e32 v37, v141, v103
	v_mul_f32_e32 v38, v142, v209
	v_mul_f32_e32 v39, v143, v242
	v_mul_f32_e32 v41, v146, v97
	v_cvt_pk_bf16_f32 v37, v37, v38
	v_cvt_pk_bf16_f32 v38, v39, v40
	v_add_co_u32_e32 v40, vcc, s2, v2
	v_mul_f32_e32 v36, v140, v247
	v_mul_f32_e32 v50, v147, v219
	v_cvt_pk_bf16_f32 v39, v41, v50
	v_addc_co_u32_e32 v41, vcc, 0, v3, vcc
	v_mul_f32_e32 v1, v139, v228
	v_cvt_pk_bf16_f32 v36, v1, v36
	global_store_dwordx4 v[40:41], v[36:39], off offset:2048 sc1
	v_mul_f32_e32 v40, v184, v68
	s_mov_b32 s2, 0x399ca000
	v_mul_f32_e32 v37, v173, v48
	v_mul_f32_e32 v38, v182, v64
	v_mul_f32_e32 v39, v183, v60
	v_mul_f32_e32 v41, v185, v89
	v_cvt_pk_bf16_f32 v37, v37, v38
	v_cvt_pk_bf16_f32 v38, v39, v40
	v_add_co_u32_e32 v40, vcc, s2, v2
	v_mul_f32_e32 v36, v172, v82
	v_mul_f32_e32 v48, v188, v52
	v_cvt_pk_bf16_f32 v39, v41, v48
	v_addc_co_u32_e32 v41, vcc, 0, v3, vcc
	v_mul_f32_e32 v1, v145, v74
	v_cvt_pk_bf16_f32 v36, v1, v36
	global_store_dwordx4 v[40:41], v[36:39], off offset:3584 sc1
	v_mul_f32_e32 v40, v192, v88
	s_mov_b32 s2, 0x399cc000
	v_mul_f32_e32 v37, v189, v86
	v_mul_f32_e32 v38, v190, v87
	v_mul_f32_e32 v39, v191, v98
	v_mul_f32_e32 v41, v193, v94
	v_cvt_pk_bf16_f32 v37, v37, v38
	v_cvt_pk_bf16_f32 v38, v39, v40
	v_add_co_u32_e32 v40, vcc, s2, v2
	v_mul_f32_e32 v48, v194, v78
	v_cvt_pk_bf16_f32 v39, v41, v48
	s_nop 0
	v_addc_co_u32_e32 v41, vcc, 0, v3, vcc
	v_add_co_u32_e32 v2, vcc, 0x399cd000, v2
	v_mul_f32_e32 v36, v187, v223
	s_nop 0
	v_addc_co_u32_e32 v3, vcc, 0, v3, vcc
	v_add_u32_e32 v181, s27, v181
	v_mul_f32_e32 v1, v186, v90
	v_cvt_pk_bf16_f32 v36, v1, v36
	v_cmp_lt_i32_e32 vcc, s33, v181
	global_store_dwordx4 v[40:41], v[36:39], off offset:1024 sc1
	v_lshl_add_u64 v[166:167], v[166:167], 0, s[16:17]
	v_lshl_add_u64 v[164:165], v[164:165], 0, s[14:15]
	v_mul_f32_e32 v36, v196, v44
	v_mul_f32_e32 v37, v197, v45
	v_mul_f32_e32 v38, v198, v46
	v_mul_f32_e32 v39, v199, v47
	v_lshl_add_u64 v[168:169], v[168:169], 0, s[18:19]
	s_or_b64 s[20:21], vcc, s[20:21]
	v_lshl_add_u64 v[170:171], v[170:171], 0, s[18:19]
	v_mul_f32_e32 v1, v195, v54
	v_mul_f32_e32 v40, v200, v49
	v_mul_f32_e32 v41, v201, v42
	v_mul_f32_e32 v42, v202, v43
	v_cvt_pk_bf16_f32 v36, v1, v36
	v_cvt_pk_bf16_f32 v37, v37, v38
	v_cvt_pk_bf16_f32 v38, v39, v40
	v_cvt_pk_bf16_f32 v39, v41, v42
	global_store_dwordx4 v[2:3], v[36:39], off offset:2560 sc1
	s_andn2_b64 exec, exec, s[20:21]
	s_cbranch_execz .LBB0_1173
